# FFN-out and out-proj residual epilogues: row sum-of-squares cross-lane reduction via v_permlane16_swap / v_permlane32_swap instead of two ds_bpermute + lgkmcnt waits per row group
# speedup vs baseline: 1.0069x; 1.0034x over previous
.LBB0_274:
	v_mbcnt_lo_u32_b32 v94, -1, 0
	v_mbcnt_hi_u32_b32 v94, -1, v94
	s_lshl_b32 s9, s25, 8
	v_ashrrev_i32_e32 v95, 1, v94
	s_lshl_b32 s7, s26, 8
	s_or_b32 s9, s9, s59
	v_and_b32_e32 v95, -8, v95
	s_add_i32 s7, s7, s58
	v_add_u32_e32 v204, s9, v95
	v_ashrrev_i32_e32 v205, 31, v204
	v_and_or_b32 v234, v94, 15, s7
	v_lshlrev_b64 v[236:237], 1, v[204:205]
	v_ashrrev_i32_e32 v235, 31, v234
	v_lshlrev_b32_e32 v244, 2, v94
	v_cmp_gt_u32_e32 vcc, 16, v94
	v_lshl_add_u64 v[94:95], s[42:43], 0, v[236:237]
	v_lshlrev_b64 v[238:239], 11, v[234:235]
	v_lshl_add_u64 v[96:97], v[94:95], 0, v[238:239]
	global_load_dwordx4 v[190:193], v[96:97], off
	global_load_dwordx4 v[186:189], v[96:97], off offset:256
	v_or_b32_e32 v230, 16, v234
	v_ashrrev_i32_e32 v231, 31, v230
	v_or_b32_e32 v210, 32, v234
	v_lshlrev_b64 v[232:233], 11, v[230:231]
	v_ashrrev_i32_e32 v211, 31, v210
	v_or_b32_e32 v226, 48, v234
	v_lshl_add_u64 v[96:97], v[94:95], 0, v[232:233]
	v_lshlrev_b64 v[212:213], 11, v[210:211]
	v_ashrrev_i32_e32 v227, 31, v226
	v_add_u32_e32 v222, 0x80, v234
	global_load_dwordx4 v[182:185], v[96:97], off
	global_load_dwordx4 v[178:181], v[96:97], off offset:256
	v_lshl_add_u64 v[96:97], v[94:95], 0, v[212:213]
	v_lshlrev_b64 v[228:229], 11, v[226:227]
	v_ashrrev_i32_e32 v223, 31, v222
	v_add_u32_e32 v218, 0x90, v234
	global_load_dwordx4 v[174:177], v[96:97], off
	global_load_dwordx4 v[170:173], v[96:97], off offset:256
	v_lshl_add_u64 v[96:97], v[94:95], 0, v[228:229]
	v_lshlrev_b64 v[224:225], 11, v[222:223]
	v_ashrrev_i32_e32 v219, 31, v218
	v_add_u32_e32 v214, 0xa0, v234
	v_add_u32_e32 v206, 0xb0, v234
	global_load_dwordx4 v[166:169], v[96:97], off
	global_load_dwordx4 v[162:165], v[96:97], off offset:256
	v_lshlrev_b64 v[220:221], 11, v[218:219]
	v_ashrrev_i32_e32 v215, 31, v214
	v_ashrrev_i32_e32 v207, 31, v206
	v_lshlrev_b64 v[216:217], 11, v[214:215]
	v_lshlrev_b64 v[208:209], 11, v[206:207]
	v_xor_b32_e32 v245, 64, v244
	v_xor_b32_e32 v244, 0x80, v244
	s_lshl_b32 s82, s25, 2
	s_ashr_i32 s83, s82, 31
	s_waitcnt vmcnt(7)
	v_lshl_add_u64 v[96:97], v[94:95], 0, v[224:225]
	global_load_dwordx4 v[158:161], v[96:97], off
	global_load_dwordx4 v[150:153], v[96:97], off offset:256
	v_lshl_add_u64 v[96:97], v[94:95], 0, v[220:221]
	global_load_dwordx4 v[142:145], v[96:97], off
	global_load_dwordx4 v[138:141], v[96:97], off offset:256
	v_lshl_add_u64 v[96:97], v[94:95], 0, v[216:217]
	v_lshl_add_u64 v[94:95], v[94:95], 0, v[208:209]
	global_load_dwordx4 v[126:129], v[96:97], off
	global_load_dwordx4 v[114:117], v[96:97], off offset:256
	global_load_dwordx4 v[106:109], v[94:95], off
	s_nop 0
	global_load_dwordx4 v[94:97], v[94:95], off offset:256
	v_lshlrev_b32_e32 v246, 16, v190
	v_and_b32_e32 v247, 0xffff0000, v190
	v_lshlrev_b32_e32 v190, 16, v191
	v_and_b32_e32 v191, 0xffff0000, v191
	v_pk_fma_f32 v[156:157], v[156:157], 0.5, v[190:191] op_sel_hi:[1,0,1]
	v_lshlrev_b32_e32 v190, 16, v192
	v_and_b32_e32 v191, 0xffff0000, v192
	v_pk_fma_f32 v[146:147], v[146:147], 0.5, v[190:191] op_sel_hi:[1,0,1]
	v_pk_fma_f32 v[154:155], v[154:155], 0.5, v[246:247] op_sel_hi:[1,0,1]
	v_pk_add_f32 v[190:191], v[146:147], 0 op_sel_hi:[1,0]
	v_lshlrev_b32_e32 v146, 16, v193
	v_and_b32_e32 v147, 0xffff0000, v193
	v_pk_add_f32 v[154:155], v[154:155], 0 op_sel_hi:[1,0]
	v_pk_fma_f32 v[146:147], v[148:149], 0.5, v[146:147] op_sel_hi:[1,0,1]
	v_pk_add_f32 v[156:157], v[156:157], 0 op_sel_hi:[1,0]
	v_pk_add_f32 v[192:193], v[146:147], 0 op_sel_hi:[1,0]
	v_cvt_pk_bf16_f32 v146, v154, v155
	v_lshl_add_u64 v[154:155], s[88:89], 0, v[238:239]
	v_cvt_pk_bf16_f32 v147, v156, v157
	v_cvt_pk_bf16_f32 v148, v190, v191
	v_cvt_pk_bf16_f32 v149, v192, v193
	v_lshl_add_u64 v[154:155], v[154:155], 0, v[236:237]
	global_store_dwordx4 v[154:155], v[146:149], off
	v_lshlrev_b32_e32 v156, 16, v146
	v_lshlrev_b32_e32 v157, 16, v147
	v_and_b32_e32 v146, 0xffff0000, v146
	v_and_b32_e32 v147, 0xffff0000, v147
	v_mul_f32_e32 v146, v146, v146
	v_mul_f32_e32 v147, v147, v147
	v_lshlrev_b32_e32 v190, 16, v148
	v_and_b32_e32 v148, 0xffff0000, v148
	v_fmac_f32_e32 v146, v156, v156
	v_fmac_f32_e32 v147, v157, v157
	v_add_f32_e32 v146, v146, v147
	v_mul_f32_e32 v147, v148, v148
	v_lshlrev_b32_e32 v191, 16, v149
	v_and_b32_e32 v149, 0xffff0000, v149
	v_fmac_f32_e32 v147, v190, v190
	v_add_f32_e32 v146, v147, v146
	v_mul_f32_e32 v147, v149, v149
	v_fmac_f32_e32 v147, v191, v191
	v_add_f32_e32 v156, v147, v146
	s_waitcnt vmcnt(15)
	v_lshlrev_b32_e32 v146, 16, v186
	v_and_b32_e32 v147, 0xffff0000, v186
	v_pk_fma_f32 v[134:135], v[134:135], 0.5, v[146:147] op_sel_hi:[1,0,1]
	v_lshlrev_b32_e32 v146, 16, v187
	v_and_b32_e32 v147, 0xffff0000, v187
	v_pk_fma_f32 v[136:137], v[136:137], 0.5, v[146:147] op_sel_hi:[1,0,1]
	v_lshlrev_b32_e32 v146, 16, v188
	v_and_b32_e32 v147, 0xffff0000, v188
	v_pk_fma_f32 v[130:131], v[130:131], 0.5, v[146:147] op_sel_hi:[1,0,1]
	v_pk_add_f32 v[134:135], v[134:135], 0 op_sel_hi:[1,0]
	v_pk_add_f32 v[146:147], v[130:131], 0 op_sel_hi:[1,0]
	v_lshlrev_b32_e32 v130, 16, v189
	v_and_b32_e32 v131, 0xffff0000, v189
	v_pk_fma_f32 v[130:131], v[132:133], 0.5, v[130:131] op_sel_hi:[1,0,1]
	v_pk_add_f32 v[136:137], v[136:137], 0 op_sel_hi:[1,0]
	v_pk_add_f32 v[148:149], v[130:131], 0 op_sel_hi:[1,0]
	v_cvt_pk_bf16_f32 v130, v134, v135
	v_cvt_pk_bf16_f32 v131, v136, v137
	v_cvt_pk_bf16_f32 v132, v146, v147
	v_cvt_pk_bf16_f32 v133, v148, v149
	global_store_dwordx4 v[154:155], v[130:133], off offset:256
	v_lshlrev_b32_e32 v134, 16, v130
	v_lshlrev_b32_e32 v135, 16, v131
	v_and_b32_e32 v130, 0xffff0000, v130
	v_and_b32_e32 v131, 0xffff0000, v131
	v_mul_f32_e32 v130, v130, v130
	v_fmac_f32_e32 v130, v134, v134
	v_mul_f32_e32 v131, v131, v131
	v_lshlrev_b32_e32 v136, 16, v132
	v_and_b32_e32 v132, 0xffff0000, v132
	v_add_f32_e32 v130, v130, v156
	v_fmac_f32_e32 v131, v135, v135
	v_add_f32_e32 v130, v131, v130
	v_mul_f32_e32 v131, v132, v132
	v_lshlrev_b32_e32 v137, 16, v133
	v_and_b32_e32 v133, 0xffff0000, v133
	v_fmac_f32_e32 v131, v136, v136
	v_add_f32_e32 v130, v131, v130
	v_mul_f32_e32 v131, v133, v133
	v_fmac_f32_e32 v131, v137, v137
	v_add_f32_e32 v130, v131, v130
	v_mov_b32_e32 v131, v130
	s_nop 1
	v_permlane16_swap_b32_e32 v131, v130
	s_waitcnt lgkmcnt(0)
	v_add_f32_e32 v130, v130, v131
	v_mov_b32_e32 v131, v130
	s_nop 1
	v_permlane32_swap_b32_e32 v131, v130
	s_and_saveexec_b64 s[48:49], vcc
	s_mov_b32 s31, 0xf800000
	s_cbranch_execz .LBB0_276
	v_lshlrev_b64 v[132:133], 6, v[234:235]
	v_lshl_add_u64 v[132:133], s[38:39], 0, v[132:133]
	v_lshl_add_u64 v[132:133], s[82:83], 2, v[132:133]
	s_lshl_b32 s76, s55, 2
	v_lshl_add_u64 v[132:133], v[132:133], 0, s[76:77]
	s_waitcnt lgkmcnt(0)
	v_add_f32_e32 v130, v130, v131
	global_store_dword v[132:133], v130, off
.LBB0_276:
	s_or_b64 exec, exec, s[48:49]
	s_waitcnt vmcnt(16)
	v_lshlrev_b32_e32 v130, 16, v182
	s_waitcnt lgkmcnt(0)
	v_and_b32_e32 v131, 0xffff0000, v182
	v_pk_fma_f32 v[122:123], v[122:123], 0.5, v[130:131] op_sel_hi:[1,0,1]
	v_lshlrev_b32_e32 v130, 16, v183
	v_and_b32_e32 v131, 0xffff0000, v183
	v_pk_fma_f32 v[124:125], v[124:125], 0.5, v[130:131] op_sel_hi:[1,0,1]
	v_lshlrev_b32_e32 v130, 16, v184
	v_and_b32_e32 v131, 0xffff0000, v184
	v_pk_fma_f32 v[118:119], v[118:119], 0.5, v[130:131] op_sel_hi:[1,0,1]
	v_pk_add_f32 v[122:123], v[122:123], 0 op_sel_hi:[1,0]
	v_pk_add_f32 v[130:131], v[118:119], 0 op_sel_hi:[1,0]
	v_lshlrev_b32_e32 v118, 16, v185
	v_and_b32_e32 v119, 0xffff0000, v185
	v_pk_fma_f32 v[118:119], v[120:121], 0.5, v[118:119] op_sel_hi:[1,0,1]
	v_pk_add_f32 v[124:125], v[124:125], 0 op_sel_hi:[1,0]
	v_pk_add_f32 v[132:133], v[118:119], 0 op_sel_hi:[1,0]
	v_cvt_pk_bf16_f32 v118, v122, v123
	v_cvt_pk_bf16_f32 v119, v124, v125
	v_and_b32_e32 v123, 0xffff0000, v118
	v_lshlrev_b32_e32 v122, 16, v118
	v_and_b32_e32 v125, 0xffff0000, v119
	v_mul_f32_e32 v123, v123, v123
	v_cvt_pk_bf16_f32 v120, v130, v131
	v_lshlrev_b32_e32 v124, 16, v119
	v_fmac_f32_e32 v123, v122, v122
	v_mul_f32_e32 v122, v125, v125
	v_and_b32_e32 v131, 0xffff0000, v120
	v_fmac_f32_e32 v122, v124, v124
	v_cvt_pk_bf16_f32 v121, v132, v133
	v_lshlrev_b32_e32 v130, 16, v120
	v_add_f32_e32 v122, v123, v122
	v_mul_f32_e32 v123, v131, v131
	v_and_b32_e32 v133, 0xffff0000, v121
	v_fmac_f32_e32 v123, v130, v130
	v_lshlrev_b32_e32 v132, 16, v121
	v_add_f32_e32 v122, v123, v122
	v_mul_f32_e32 v123, v133, v133
	v_fmac_f32_e32 v123, v132, v132
	v_add_f32_e32 v124, v123, v122
	s_waitcnt vmcnt(15)
	v_lshlrev_b32_e32 v122, 16, v178
	v_and_b32_e32 v123, 0xffff0000, v178
	v_pk_fma_f32 v[110:111], v[110:111], 0.5, v[122:123] op_sel_hi:[1,0,1]
	v_lshlrev_b32_e32 v122, 16, v179
	v_and_b32_e32 v123, 0xffff0000, v179
	v_pk_fma_f32 v[112:113], v[112:113], 0.5, v[122:123] op_sel_hi:[1,0,1]
	v_lshlrev_b32_e32 v122, 16, v180
	v_and_b32_e32 v123, 0xffff0000, v180
	v_pk_add_f32 v[110:111], v[110:111], 0 op_sel_hi:[1,0]
	v_pk_fma_f32 v[102:103], v[102:103], 0.5, v[122:123] op_sel_hi:[1,0,1]
	v_pk_add_f32 v[112:113], v[112:113], 0 op_sel_hi:[1,0]
	v_pk_add_f32 v[102:103], v[102:103], 0 op_sel_hi:[1,0]
	v_lshlrev_b32_e32 v122, 16, v181
	v_and_b32_e32 v123, 0xffff0000, v181
	v_cvt_pk_bf16_f32 v110, v110, v111
	v_pk_fma_f32 v[104:105], v[104:105], 0.5, v[122:123] op_sel_hi:[1,0,1]
	v_cvt_pk_bf16_f32 v111, v112, v113
	v_cvt_pk_bf16_f32 v112, v102, v103
	v_and_b32_e32 v103, 0xffff0000, v110
	v_pk_add_f32 v[104:105], v[104:105], 0 op_sel_hi:[1,0]
	v_lshlrev_b32_e32 v102, 16, v110
	v_mul_f32_e32 v103, v103, v103
	v_cvt_pk_bf16_f32 v113, v104, v105
	v_and_b32_e32 v105, 0xffff0000, v111
	v_fmac_f32_e32 v103, v102, v102
	v_lshlrev_b32_e32 v104, 16, v111
	v_add_f32_e32 v102, v103, v124
	v_mul_f32_e32 v103, v105, v105
	v_and_b32_e32 v123, 0xffff0000, v112
	v_fmac_f32_e32 v103, v104, v104
	v_lshlrev_b32_e32 v122, 16, v112
	v_add_f32_e32 v102, v103, v102
	v_mul_f32_e32 v103, v123, v123
	v_and_b32_e32 v130, 0xffff0000, v113
	v_fmac_f32_e32 v103, v122, v122
	v_lshlrev_b32_e32 v125, 16, v113
	v_add_f32_e32 v102, v103, v102
	v_mul_f32_e32 v103, v130, v130
	v_fmac_f32_e32 v103, v125, v125
	v_add_f32_e32 v102, v103, v102
	v_mov_b32_e32 v103, v102
	s_nop 1
	v_permlane16_swap_b32_e32 v103, v102
	v_lshl_add_u64 v[104:105], s[88:89], 0, v[232:233]
	v_lshl_add_u64 v[104:105], v[204:205], 1, v[104:105]
	global_store_dwordx4 v[104:105], v[118:121], off
	global_store_dwordx4 v[104:105], v[110:113], off offset:256
	s_waitcnt lgkmcnt(0)
	v_add_f32_e32 v102, v102, v103
	v_mov_b32_e32 v103, v102
	s_nop 1
	v_permlane32_swap_b32_e32 v103, v102
	s_and_saveexec_b64 s[48:49], vcc
	s_cbranch_execz .LBB0_278
	v_lshlrev_b64 v[104:105], 6, v[230:231]
	v_lshl_add_u64 v[104:105], s[38:39], 0, v[104:105]
	v_lshl_add_u64 v[104:105], s[82:83], 2, v[104:105]
	s_lshl_b32 s76, s55, 2
	v_lshl_add_u64 v[104:105], v[104:105], 0, s[76:77]
	s_waitcnt lgkmcnt(0)
	v_add_f32_e32 v102, v102, v103
	global_store_dword v[104:105], v102, off
.LBB0_278:
	s_or_b64 exec, exec, s[48:49]
	s_waitcnt vmcnt(17)
	v_lshlrev_b32_e32 v102, 16, v174
	s_waitcnt lgkmcnt(0)
	v_and_b32_e32 v103, 0xffff0000, v174
	v_pk_fma_f32 v[98:99], v[98:99], 0.5, v[102:103] op_sel_hi:[1,0,1]
	v_lshlrev_b32_e32 v102, 16, v175
	v_and_b32_e32 v103, 0xffff0000, v175
	v_pk_fma_f32 v[100:101], v[100:101], 0.5, v[102:103] op_sel_hi:[1,0,1]
	v_lshlrev_b32_e32 v102, 16, v176
	v_and_b32_e32 v103, 0xffff0000, v176
	v_pk_fma_f32 v[90:91], v[90:91], 0.5, v[102:103] op_sel_hi:[1,0,1]
	v_pk_add_f32 v[98:99], v[98:99], 0 op_sel_hi:[1,0]
	v_pk_add_f32 v[102:103], v[90:91], 0 op_sel_hi:[1,0]
	v_lshlrev_b32_e32 v90, 16, v177
	v_and_b32_e32 v91, 0xffff0000, v177
	v_pk_fma_f32 v[90:91], v[92:93], 0.5, v[90:91] op_sel_hi:[1,0,1]
	v_pk_add_f32 v[100:101], v[100:101], 0 op_sel_hi:[1,0]
	v_pk_add_f32 v[104:105], v[90:91], 0 op_sel_hi:[1,0]
	v_cvt_pk_bf16_f32 v90, v98, v99
	v_cvt_pk_bf16_f32 v91, v100, v101
	v_and_b32_e32 v99, 0xffff0000, v90
	v_lshlrev_b32_e32 v98, 16, v90
	v_and_b32_e32 v101, 0xffff0000, v91
	v_mul_f32_e32 v99, v99, v99
	v_cvt_pk_bf16_f32 v92, v102, v103
	v_lshlrev_b32_e32 v100, 16, v91
	v_fmac_f32_e32 v99, v98, v98
	v_mul_f32_e32 v98, v101, v101
	v_and_b32_e32 v103, 0xffff0000, v92
	v_fmac_f32_e32 v98, v100, v100
	v_cvt_pk_bf16_f32 v93, v104, v105
	v_lshlrev_b32_e32 v102, 16, v92
	v_add_f32_e32 v98, v99, v98
	v_mul_f32_e32 v99, v103, v103
	v_and_b32_e32 v105, 0xffff0000, v93
	v_fmac_f32_e32 v99, v102, v102
	v_lshlrev_b32_e32 v104, 16, v93
	v_add_f32_e32 v98, v99, v98
	v_mul_f32_e32 v99, v105, v105
	v_fmac_f32_e32 v99, v104, v104
	v_add_f32_e32 v100, v99, v98
	s_waitcnt vmcnt(16)
	v_lshlrev_b32_e32 v98, 16, v170
	v_and_b32_e32 v99, 0xffff0000, v170
	v_pk_fma_f32 v[86:87], v[86:87], 0.5, v[98:99] op_sel_hi:[1,0,1]
	v_lshlrev_b32_e32 v98, 16, v171
	v_and_b32_e32 v99, 0xffff0000, v171
	v_pk_fma_f32 v[88:89], v[88:89], 0.5, v[98:99] op_sel_hi:[1,0,1]
	v_lshlrev_b32_e32 v98, 16, v172
	v_and_b32_e32 v99, 0xffff0000, v172
	v_pk_fma_f32 v[82:83], v[82:83], 0.5, v[98:99] op_sel_hi:[1,0,1]
	v_lshlrev_b32_e32 v98, 16, v173
	v_and_b32_e32 v99, 0xffff0000, v173
	v_pk_add_f32 v[86:87], v[86:87], 0 op_sel_hi:[1,0]
	v_pk_fma_f32 v[84:85], v[84:85], 0.5, v[98:99] op_sel_hi:[1,0,1]
	v_pk_add_f32 v[82:83], v[82:83], 0 op_sel_hi:[1,0]
	v_pk_add_f32 v[98:99], v[84:85], 0 op_sel_hi:[1,0]
	v_cvt_pk_bf16_f32 v84, v86, v87
	v_pk_add_f32 v[88:89], v[88:89], 0 op_sel_hi:[1,0]
	v_cvt_pk_bf16_f32 v86, v82, v83
	v_and_b32_e32 v83, 0xffff0000, v84
	v_cvt_pk_bf16_f32 v85, v88, v89
	v_lshlrev_b32_e32 v82, 16, v84
	v_mul_f32_e32 v83, v83, v83
	v_and_b32_e32 v89, 0xffff0000, v85
	v_fmac_f32_e32 v83, v82, v82
	v_lshlrev_b32_e32 v88, 16, v85
	v_add_f32_e32 v82, v83, v100
	v_mul_f32_e32 v83, v89, v89
	v_cvt_pk_bf16_f32 v87, v98, v99
	v_and_b32_e32 v99, 0xffff0000, v86
	v_fmac_f32_e32 v83, v88, v88
	v_lshlrev_b32_e32 v98, 16, v86
	v_add_f32_e32 v82, v83, v82
	v_mul_f32_e32 v83, v99, v99
	v_and_b32_e32 v102, 0xffff0000, v87
	v_fmac_f32_e32 v83, v98, v98
	v_lshlrev_b32_e32 v101, 16, v87
	v_add_f32_e32 v82, v83, v82
	v_mul_f32_e32 v83, v102, v102
	v_fmac_f32_e32 v83, v101, v101
	v_add_f32_e32 v82, v83, v82
	v_mov_b32_e32 v83, v82
	s_nop 1
	v_permlane16_swap_b32_e32 v83, v82
	v_lshl_add_u64 v[88:89], s[88:89], 0, v[212:213]
	v_lshl_add_u64 v[88:89], v[204:205], 1, v[88:89]
	global_store_dwordx4 v[88:89], v[90:93], off
	global_store_dwordx4 v[88:89], v[84:87], off offset:256
	s_waitcnt lgkmcnt(0)
	v_add_f32_e32 v82, v82, v83
	v_mov_b32_e32 v83, v82
	s_nop 1
	v_permlane32_swap_b32_e32 v83, v82
	s_and_saveexec_b64 s[48:49], vcc
	s_cbranch_execz .LBB0_280
	v_lshlrev_b64 v[84:85], 6, v[210:211]
	v_lshl_add_u64 v[84:85], s[38:39], 0, v[84:85]
	v_lshl_add_u64 v[84:85], s[82:83], 2, v[84:85]
	s_lshl_b32 s76, s55, 2
	v_lshl_add_u64 v[84:85], v[84:85], 0, s[76:77]
	s_waitcnt lgkmcnt(0)
	v_add_f32_e32 v82, v82, v83
	global_store_dword v[84:85], v82, off
.LBB0_280:
	s_or_b64 exec, exec, s[48:49]
	s_waitcnt vmcnt(18)
	v_lshlrev_b32_e32 v82, 16, v166
	s_waitcnt lgkmcnt(0)
	v_and_b32_e32 v83, 0xffff0000, v166
	v_pk_fma_f32 v[78:79], v[78:79], 0.5, v[82:83] op_sel_hi:[1,0,1]
	v_lshlrev_b32_e32 v82, 16, v167
	v_and_b32_e32 v83, 0xffff0000, v167
	v_pk_fma_f32 v[80:81], v[80:81], 0.5, v[82:83] op_sel_hi:[1,0,1]
	v_lshlrev_b32_e32 v82, 16, v168
	v_and_b32_e32 v83, 0xffff0000, v168
	v_pk_fma_f32 v[74:75], v[74:75], 0.5, v[82:83] op_sel_hi:[1,0,1]
	v_pk_add_f32 v[78:79], v[78:79], 0 op_sel_hi:[1,0]
	v_pk_add_f32 v[82:83], v[74:75], 0 op_sel_hi:[1,0]
	v_lshlrev_b32_e32 v74, 16, v169
	v_and_b32_e32 v75, 0xffff0000, v169
	v_pk_fma_f32 v[74:75], v[76:77], 0.5, v[74:75] op_sel_hi:[1,0,1]
	v_pk_add_f32 v[80:81], v[80:81], 0 op_sel_hi:[1,0]
	v_pk_add_f32 v[84:85], v[74:75], 0 op_sel_hi:[1,0]
	v_cvt_pk_bf16_f32 v74, v78, v79
	v_cvt_pk_bf16_f32 v75, v80, v81
	v_and_b32_e32 v79, 0xffff0000, v74
	v_lshlrev_b32_e32 v78, 16, v74
	v_and_b32_e32 v81, 0xffff0000, v75
	v_mul_f32_e32 v79, v79, v79
	v_cvt_pk_bf16_f32 v76, v82, v83
	v_lshlrev_b32_e32 v80, 16, v75
	v_fmac_f32_e32 v79, v78, v78
	v_mul_f32_e32 v78, v81, v81
	v_and_b32_e32 v83, 0xffff0000, v76
	v_fmac_f32_e32 v78, v80, v80
	v_cvt_pk_bf16_f32 v77, v84, v85
	v_lshlrev_b32_e32 v82, 16, v76
	v_add_f32_e32 v78, v79, v78
	v_mul_f32_e32 v79, v83, v83
	v_and_b32_e32 v85, 0xffff0000, v77
	v_fmac_f32_e32 v79, v82, v82
	v_lshlrev_b32_e32 v84, 16, v77
	v_add_f32_e32 v78, v79, v78
	v_mul_f32_e32 v79, v85, v85
	v_fmac_f32_e32 v79, v84, v84
	v_add_f32_e32 v80, v79, v78
	s_waitcnt vmcnt(17)
	v_lshlrev_b32_e32 v78, 16, v162
	v_and_b32_e32 v79, 0xffff0000, v162
	v_pk_fma_f32 v[70:71], v[70:71], 0.5, v[78:79] op_sel_hi:[1,0,1]
	v_lshlrev_b32_e32 v78, 16, v163
	v_and_b32_e32 v79, 0xffff0000, v163
	v_pk_fma_f32 v[72:73], v[72:73], 0.5, v[78:79] op_sel_hi:[1,0,1]
	v_lshlrev_b32_e32 v78, 16, v164
	v_and_b32_e32 v79, 0xffff0000, v164
	v_pk_fma_f32 v[66:67], v[66:67], 0.5, v[78:79] op_sel_hi:[1,0,1]
	v_lshlrev_b32_e32 v78, 16, v165
	v_and_b32_e32 v79, 0xffff0000, v165
	v_pk_add_f32 v[70:71], v[70:71], 0 op_sel_hi:[1,0]
	v_pk_fma_f32 v[68:69], v[68:69], 0.5, v[78:79] op_sel_hi:[1,0,1]
	v_pk_add_f32 v[66:67], v[66:67], 0 op_sel_hi:[1,0]
	v_pk_add_f32 v[78:79], v[68:69], 0 op_sel_hi:[1,0]
	v_cvt_pk_bf16_f32 v68, v70, v71
	v_pk_add_f32 v[72:73], v[72:73], 0 op_sel_hi:[1,0]
	v_cvt_pk_bf16_f32 v70, v66, v67
	v_and_b32_e32 v67, 0xffff0000, v68
	v_cvt_pk_bf16_f32 v69, v72, v73
	v_lshlrev_b32_e32 v66, 16, v68
	v_mul_f32_e32 v67, v67, v67
	v_and_b32_e32 v73, 0xffff0000, v69
	v_fmac_f32_e32 v67, v66, v66
	v_lshlrev_b32_e32 v72, 16, v69
	v_add_f32_e32 v66, v67, v80
	v_mul_f32_e32 v67, v73, v73
	v_cvt_pk_bf16_f32 v71, v78, v79
	v_and_b32_e32 v79, 0xffff0000, v70
	v_fmac_f32_e32 v67, v72, v72
	v_lshlrev_b32_e32 v78, 16, v70
	v_add_f32_e32 v66, v67, v66
	v_mul_f32_e32 v67, v79, v79
	v_and_b32_e32 v82, 0xffff0000, v71
	v_fmac_f32_e32 v67, v78, v78
	v_lshlrev_b32_e32 v81, 16, v71
	v_add_f32_e32 v66, v67, v66
	v_mul_f32_e32 v67, v82, v82
	v_fmac_f32_e32 v67, v81, v81
	v_add_f32_e32 v66, v67, v66
	v_mov_b32_e32 v67, v66
	s_nop 1
	v_permlane16_swap_b32_e32 v67, v66
	v_lshl_add_u64 v[72:73], s[88:89], 0, v[228:229]
	v_lshl_add_u64 v[72:73], v[204:205], 1, v[72:73]
	global_store_dwordx4 v[72:73], v[74:77], off
	global_store_dwordx4 v[72:73], v[68:71], off offset:256
	s_waitcnt lgkmcnt(0)
	v_add_f32_e32 v66, v66, v67
	v_mov_b32_e32 v67, v66
	s_nop 1
	v_permlane32_swap_b32_e32 v67, v66
	s_and_saveexec_b64 s[48:49], vcc
	s_cbranch_execz .LBB0_282
	v_lshlrev_b64 v[68:69], 6, v[226:227]
	v_lshl_add_u64 v[68:69], s[38:39], 0, v[68:69]
	v_lshl_add_u64 v[68:69], s[82:83], 2, v[68:69]
	s_lshl_b32 s76, s55, 2
	v_lshl_add_u64 v[68:69], v[68:69], 0, s[76:77]
	s_waitcnt lgkmcnt(0)
	v_add_f32_e32 v66, v66, v67
	global_store_dword v[68:69], v66, off
.LBB0_282:
	s_or_b64 exec, exec, s[48:49]
	s_waitcnt vmcnt(19)
	v_lshlrev_b32_e32 v66, 16, v158
	s_waitcnt lgkmcnt(0)
	v_and_b32_e32 v67, 0xffff0000, v158
	v_pk_fma_f32 v[62:63], v[62:63], 0.5, v[66:67] op_sel_hi:[1,0,1]
	v_lshlrev_b32_e32 v66, 16, v159
	v_and_b32_e32 v67, 0xffff0000, v159
	v_pk_fma_f32 v[64:65], v[64:65], 0.5, v[66:67] op_sel_hi:[1,0,1]
	v_lshlrev_b32_e32 v66, 16, v160
	v_and_b32_e32 v67, 0xffff0000, v160
	v_pk_fma_f32 v[58:59], v[58:59], 0.5, v[66:67] op_sel_hi:[1,0,1]
	v_pk_add_f32 v[62:63], v[62:63], 0 op_sel_hi:[1,0]
	v_pk_add_f32 v[66:67], v[58:59], 0 op_sel_hi:[1,0]
	v_lshlrev_b32_e32 v58, 16, v161
	v_and_b32_e32 v59, 0xffff0000, v161
	v_pk_fma_f32 v[58:59], v[60:61], 0.5, v[58:59] op_sel_hi:[1,0,1]
	v_pk_add_f32 v[64:65], v[64:65], 0 op_sel_hi:[1,0]
	v_pk_add_f32 v[68:69], v[58:59], 0 op_sel_hi:[1,0]
	v_cvt_pk_bf16_f32 v58, v62, v63
	v_cvt_pk_bf16_f32 v59, v64, v65
	v_and_b32_e32 v63, 0xffff0000, v58
	v_lshlrev_b32_e32 v62, 16, v58
	v_and_b32_e32 v65, 0xffff0000, v59
	v_mul_f32_e32 v63, v63, v63
	v_cvt_pk_bf16_f32 v60, v66, v67
	v_lshlrev_b32_e32 v64, 16, v59
	v_fmac_f32_e32 v63, v62, v62
	v_mul_f32_e32 v62, v65, v65
	v_and_b32_e32 v67, 0xffff0000, v60
	v_fmac_f32_e32 v62, v64, v64
	v_cvt_pk_bf16_f32 v61, v68, v69
	v_lshlrev_b32_e32 v66, 16, v60
	v_add_f32_e32 v62, v63, v62
	v_mul_f32_e32 v63, v67, v67
	v_and_b32_e32 v69, 0xffff0000, v61
	v_fmac_f32_e32 v63, v66, v66
	v_lshlrev_b32_e32 v68, 16, v61
	v_add_f32_e32 v62, v63, v62
	v_mul_f32_e32 v63, v69, v69
	v_fmac_f32_e32 v63, v68, v68
	v_add_f32_e32 v64, v63, v62
	s_waitcnt vmcnt(18)
	v_lshlrev_b32_e32 v62, 16, v150
	v_and_b32_e32 v63, 0xffff0000, v150
	v_pk_fma_f32 v[54:55], v[54:55], 0.5, v[62:63] op_sel_hi:[1,0,1]
	v_lshlrev_b32_e32 v62, 16, v151
	v_and_b32_e32 v63, 0xffff0000, v151
	v_pk_fma_f32 v[56:57], v[56:57], 0.5, v[62:63] op_sel_hi:[1,0,1]
	v_lshlrev_b32_e32 v62, 16, v152
	v_and_b32_e32 v63, 0xffff0000, v152
	v_pk_fma_f32 v[50:51], v[50:51], 0.5, v[62:63] op_sel_hi:[1,0,1]
	v_lshlrev_b32_e32 v62, 16, v153
	v_and_b32_e32 v63, 0xffff0000, v153
	v_pk_add_f32 v[54:55], v[54:55], 0 op_sel_hi:[1,0]
	v_pk_fma_f32 v[52:53], v[52:53], 0.5, v[62:63] op_sel_hi:[1,0,1]
	v_pk_add_f32 v[50:51], v[50:51], 0 op_sel_hi:[1,0]
	v_pk_add_f32 v[62:63], v[52:53], 0 op_sel_hi:[1,0]
	v_cvt_pk_bf16_f32 v52, v54, v55
	v_pk_add_f32 v[56:57], v[56:57], 0 op_sel_hi:[1,0]
	v_cvt_pk_bf16_f32 v54, v50, v51
	v_and_b32_e32 v51, 0xffff0000, v52
	v_cvt_pk_bf16_f32 v53, v56, v57
	v_lshlrev_b32_e32 v50, 16, v52
	v_mul_f32_e32 v51, v51, v51
	v_and_b32_e32 v57, 0xffff0000, v53
	v_fmac_f32_e32 v51, v50, v50
	v_lshlrev_b32_e32 v56, 16, v53
	v_add_f32_e32 v50, v51, v64
	v_mul_f32_e32 v51, v57, v57
	v_cvt_pk_bf16_f32 v55, v62, v63
	v_and_b32_e32 v63, 0xffff0000, v54
	v_fmac_f32_e32 v51, v56, v56
	v_lshlrev_b32_e32 v62, 16, v54
	v_add_f32_e32 v50, v51, v50
	v_mul_f32_e32 v51, v63, v63
	v_and_b32_e32 v66, 0xffff0000, v55
	v_fmac_f32_e32 v51, v62, v62
	v_lshlrev_b32_e32 v65, 16, v55
	v_add_f32_e32 v50, v51, v50
	v_mul_f32_e32 v51, v66, v66
	v_fmac_f32_e32 v51, v65, v65
	v_add_f32_e32 v50, v51, v50
	v_mov_b32_e32 v51, v50
	s_nop 1
	v_permlane16_swap_b32_e32 v51, v50
	v_lshl_add_u64 v[56:57], s[88:89], 0, v[224:225]
	v_lshl_add_u64 v[56:57], v[204:205], 1, v[56:57]
	global_store_dwordx4 v[56:57], v[58:61], off
	global_store_dwordx4 v[56:57], v[52:55], off offset:256
	s_waitcnt lgkmcnt(0)
	v_add_f32_e32 v50, v50, v51
	v_mov_b32_e32 v51, v50
	s_nop 1
	v_permlane32_swap_b32_e32 v51, v50
	s_and_saveexec_b64 s[48:49], vcc
	s_cbranch_execz .LBB0_284
	v_lshlrev_b64 v[52:53], 6, v[222:223]
	v_lshl_add_u64 v[52:53], s[38:39], 0, v[52:53]
	v_lshl_add_u64 v[52:53], s[82:83], 2, v[52:53]
	s_lshl_b32 s76, s55, 2
	v_lshl_add_u64 v[52:53], v[52:53], 0, s[76:77]
	s_waitcnt lgkmcnt(0)
	v_add_f32_e32 v50, v50, v51
	global_store_dword v[52:53], v50, off
.LBB0_284:
	s_or_b64 exec, exec, s[48:49]
	s_waitcnt vmcnt(20)
	v_lshlrev_b32_e32 v50, 16, v142
	s_waitcnt lgkmcnt(0)
	v_and_b32_e32 v51, 0xffff0000, v142
	v_pk_fma_f32 v[46:47], v[46:47], 0.5, v[50:51] op_sel_hi:[1,0,1]
	v_lshlrev_b32_e32 v50, 16, v143
	v_and_b32_e32 v51, 0xffff0000, v143
	v_pk_fma_f32 v[48:49], v[48:49], 0.5, v[50:51] op_sel_hi:[1,0,1]
	v_lshlrev_b32_e32 v50, 16, v144
	v_and_b32_e32 v51, 0xffff0000, v144
	v_pk_fma_f32 v[42:43], v[42:43], 0.5, v[50:51] op_sel_hi:[1,0,1]
	v_pk_add_f32 v[46:47], v[46:47], 0 op_sel_hi:[1,0]
	v_pk_add_f32 v[50:51], v[42:43], 0 op_sel_hi:[1,0]
	v_lshlrev_b32_e32 v42, 16, v145
	v_and_b32_e32 v43, 0xffff0000, v145
	v_pk_fma_f32 v[42:43], v[44:45], 0.5, v[42:43] op_sel_hi:[1,0,1]
	v_pk_add_f32 v[48:49], v[48:49], 0 op_sel_hi:[1,0]
	v_pk_add_f32 v[52:53], v[42:43], 0 op_sel_hi:[1,0]
	v_cvt_pk_bf16_f32 v42, v46, v47
	v_cvt_pk_bf16_f32 v43, v48, v49
	v_and_b32_e32 v47, 0xffff0000, v42
	v_lshlrev_b32_e32 v46, 16, v42
	v_and_b32_e32 v49, 0xffff0000, v43
	v_mul_f32_e32 v47, v47, v47
	v_cvt_pk_bf16_f32 v44, v50, v51
	v_lshlrev_b32_e32 v48, 16, v43
	v_fmac_f32_e32 v47, v46, v46
	v_mul_f32_e32 v46, v49, v49
	v_and_b32_e32 v51, 0xffff0000, v44
	v_fmac_f32_e32 v46, v48, v48
	v_cvt_pk_bf16_f32 v45, v52, v53
	v_lshlrev_b32_e32 v50, 16, v44
	v_add_f32_e32 v46, v47, v46
	v_mul_f32_e32 v47, v51, v51
	v_and_b32_e32 v53, 0xffff0000, v45
	v_fmac_f32_e32 v47, v50, v50
	v_lshlrev_b32_e32 v52, 16, v45
	v_add_f32_e32 v46, v47, v46
	v_mul_f32_e32 v47, v53, v53
	v_fmac_f32_e32 v47, v52, v52
	v_add_f32_e32 v48, v47, v46
	s_waitcnt vmcnt(19)
	v_lshlrev_b32_e32 v46, 16, v138
	v_and_b32_e32 v47, 0xffff0000, v138
	v_pk_fma_f32 v[38:39], v[38:39], 0.5, v[46:47] op_sel_hi:[1,0,1]
	v_lshlrev_b32_e32 v46, 16, v139
	v_and_b32_e32 v47, 0xffff0000, v139
	v_pk_fma_f32 v[40:41], v[40:41], 0.5, v[46:47] op_sel_hi:[1,0,1]
	v_lshlrev_b32_e32 v46, 16, v140
	v_and_b32_e32 v47, 0xffff0000, v140
	v_pk_fma_f32 v[34:35], v[34:35], 0.5, v[46:47] op_sel_hi:[1,0,1]
	v_lshlrev_b32_e32 v46, 16, v141
	v_and_b32_e32 v47, 0xffff0000, v141
	v_pk_add_f32 v[38:39], v[38:39], 0 op_sel_hi:[1,0]
	v_pk_fma_f32 v[36:37], v[36:37], 0.5, v[46:47] op_sel_hi:[1,0,1]
	v_pk_add_f32 v[34:35], v[34:35], 0 op_sel_hi:[1,0]
	v_pk_add_f32 v[46:47], v[36:37], 0 op_sel_hi:[1,0]
	v_cvt_pk_bf16_f32 v36, v38, v39
	v_pk_add_f32 v[40:41], v[40:41], 0 op_sel_hi:[1,0]
	v_cvt_pk_bf16_f32 v38, v34, v35
	v_and_b32_e32 v35, 0xffff0000, v36
	v_cvt_pk_bf16_f32 v37, v40, v41
	v_lshlrev_b32_e32 v34, 16, v36
	v_mul_f32_e32 v35, v35, v35
	v_and_b32_e32 v41, 0xffff0000, v37
	v_fmac_f32_e32 v35, v34, v34
	v_lshlrev_b32_e32 v40, 16, v37
	v_add_f32_e32 v34, v35, v48
	v_mul_f32_e32 v35, v41, v41
	v_cvt_pk_bf16_f32 v39, v46, v47
	v_and_b32_e32 v47, 0xffff0000, v38
	v_fmac_f32_e32 v35, v40, v40
	v_lshlrev_b32_e32 v46, 16, v38
	v_add_f32_e32 v34, v35, v34
	v_mul_f32_e32 v35, v47, v47
	v_and_b32_e32 v50, 0xffff0000, v39
	v_fmac_f32_e32 v35, v46, v46
	v_lshlrev_b32_e32 v49, 16, v39
	v_add_f32_e32 v34, v35, v34
	v_mul_f32_e32 v35, v50, v50
	v_fmac_f32_e32 v35, v49, v49
	v_add_f32_e32 v34, v35, v34
	v_mov_b32_e32 v35, v34
	s_nop 1
	v_permlane16_swap_b32_e32 v35, v34
	v_lshl_add_u64 v[40:41], s[88:89], 0, v[220:221]
	v_lshl_add_u64 v[40:41], v[204:205], 1, v[40:41]
	global_store_dwordx4 v[40:41], v[42:45], off
	global_store_dwordx4 v[40:41], v[36:39], off offset:256
	s_waitcnt lgkmcnt(0)
	v_add_f32_e32 v34, v34, v35
	v_mov_b32_e32 v35, v34
	s_nop 1
	v_permlane32_swap_b32_e32 v35, v34
	s_and_saveexec_b64 s[48:49], vcc
	s_cbranch_execz .LBB0_286
	v_lshlrev_b64 v[36:37], 6, v[218:219]
	v_lshl_add_u64 v[36:37], s[38:39], 0, v[36:37]
	v_lshl_add_u64 v[36:37], s[82:83], 2, v[36:37]
	s_lshl_b32 s76, s55, 2
	v_lshl_add_u64 v[36:37], v[36:37], 0, s[76:77]
	s_waitcnt lgkmcnt(0)
	v_add_f32_e32 v34, v34, v35
	global_store_dword v[36:37], v34, off
.LBB0_286:
	s_or_b64 exec, exec, s[48:49]
	s_waitcnt vmcnt(21)
	v_lshlrev_b32_e32 v34, 16, v126
	s_waitcnt lgkmcnt(0)
	v_and_b32_e32 v35, 0xffff0000, v126
	v_pk_fma_f32 v[30:31], v[30:31], 0.5, v[34:35] op_sel_hi:[1,0,1]
	v_lshlrev_b32_e32 v34, 16, v127
	v_and_b32_e32 v35, 0xffff0000, v127
	v_pk_fma_f32 v[32:33], v[32:33], 0.5, v[34:35] op_sel_hi:[1,0,1]
	v_lshlrev_b32_e32 v34, 16, v128
	v_and_b32_e32 v35, 0xffff0000, v128
	v_pk_fma_f32 v[26:27], v[26:27], 0.5, v[34:35] op_sel_hi:[1,0,1]
	v_pk_add_f32 v[30:31], v[30:31], 0 op_sel_hi:[1,0]
	v_pk_add_f32 v[34:35], v[26:27], 0 op_sel_hi:[1,0]
	v_lshlrev_b32_e32 v26, 16, v129
	v_and_b32_e32 v27, 0xffff0000, v129
	v_pk_fma_f32 v[26:27], v[28:29], 0.5, v[26:27] op_sel_hi:[1,0,1]
	v_pk_add_f32 v[32:33], v[32:33], 0 op_sel_hi:[1,0]
	v_pk_add_f32 v[36:37], v[26:27], 0 op_sel_hi:[1,0]
	v_cvt_pk_bf16_f32 v26, v30, v31
	v_cvt_pk_bf16_f32 v27, v32, v33
	v_and_b32_e32 v31, 0xffff0000, v26
	v_lshlrev_b32_e32 v30, 16, v26
	v_and_b32_e32 v33, 0xffff0000, v27
	v_mul_f32_e32 v31, v31, v31
	v_cvt_pk_bf16_f32 v28, v34, v35
	v_lshlrev_b32_e32 v32, 16, v27
	v_fmac_f32_e32 v31, v30, v30
	v_mul_f32_e32 v30, v33, v33
	v_and_b32_e32 v35, 0xffff0000, v28
	v_fmac_f32_e32 v30, v32, v32
	v_cvt_pk_bf16_f32 v29, v36, v37
	v_lshlrev_b32_e32 v34, 16, v28
	v_add_f32_e32 v30, v31, v30
	v_mul_f32_e32 v31, v35, v35
	v_and_b32_e32 v37, 0xffff0000, v29
	v_fmac_f32_e32 v31, v34, v34
	v_lshlrev_b32_e32 v36, 16, v29
	v_add_f32_e32 v30, v31, v30
	v_mul_f32_e32 v31, v37, v37
	v_fmac_f32_e32 v31, v36, v36
	v_add_f32_e32 v32, v31, v30
	s_waitcnt vmcnt(20)
	v_lshlrev_b32_e32 v30, 16, v114
	v_and_b32_e32 v31, 0xffff0000, v114
	v_pk_fma_f32 v[22:23], v[22:23], 0.5, v[30:31] op_sel_hi:[1,0,1]
	v_lshlrev_b32_e32 v30, 16, v115
	v_and_b32_e32 v31, 0xffff0000, v115
	v_pk_fma_f32 v[24:25], v[24:25], 0.5, v[30:31] op_sel_hi:[1,0,1]
	v_lshlrev_b32_e32 v30, 16, v116
	v_and_b32_e32 v31, 0xffff0000, v116
	v_pk_fma_f32 v[18:19], v[18:19], 0.5, v[30:31] op_sel_hi:[1,0,1]
	v_lshlrev_b32_e32 v30, 16, v117
	v_and_b32_e32 v31, 0xffff0000, v117
	v_pk_add_f32 v[22:23], v[22:23], 0 op_sel_hi:[1,0]
	v_pk_fma_f32 v[20:21], v[20:21], 0.5, v[30:31] op_sel_hi:[1,0,1]
	v_pk_add_f32 v[18:19], v[18:19], 0 op_sel_hi:[1,0]
	v_pk_add_f32 v[30:31], v[20:21], 0 op_sel_hi:[1,0]
	v_cvt_pk_bf16_f32 v20, v22, v23
	v_pk_add_f32 v[24:25], v[24:25], 0 op_sel_hi:[1,0]
	v_cvt_pk_bf16_f32 v22, v18, v19
	v_and_b32_e32 v19, 0xffff0000, v20
	v_cvt_pk_bf16_f32 v21, v24, v25
	v_lshlrev_b32_e32 v18, 16, v20
	v_mul_f32_e32 v19, v19, v19
	v_and_b32_e32 v25, 0xffff0000, v21
	v_fmac_f32_e32 v19, v18, v18
	v_lshlrev_b32_e32 v24, 16, v21
	v_add_f32_e32 v18, v19, v32
	v_mul_f32_e32 v19, v25, v25
	v_cvt_pk_bf16_f32 v23, v30, v31
	v_and_b32_e32 v31, 0xffff0000, v22
	v_fmac_f32_e32 v19, v24, v24
	v_lshlrev_b32_e32 v30, 16, v22
	v_add_f32_e32 v18, v19, v18
	v_mul_f32_e32 v19, v31, v31
	v_and_b32_e32 v34, 0xffff0000, v23
	v_fmac_f32_e32 v19, v30, v30
	v_lshlrev_b32_e32 v33, 16, v23
	v_add_f32_e32 v18, v19, v18
	v_mul_f32_e32 v19, v34, v34
	v_fmac_f32_e32 v19, v33, v33
	v_add_f32_e32 v18, v19, v18
	v_mov_b32_e32 v19, v18
	s_nop 1
	v_permlane16_swap_b32_e32 v19, v18
	v_lshl_add_u64 v[24:25], s[88:89], 0, v[216:217]
	v_lshl_add_u64 v[24:25], v[204:205], 1, v[24:25]
	global_store_dwordx4 v[24:25], v[26:29], off
	global_store_dwordx4 v[24:25], v[20:23], off offset:256
	s_waitcnt lgkmcnt(0)
	v_add_f32_e32 v18, v18, v19
	v_mov_b32_e32 v19, v18
	s_nop 1
	v_permlane32_swap_b32_e32 v19, v18
	s_and_saveexec_b64 s[48:49], vcc
	s_cbranch_execz .LBB0_288
	v_lshlrev_b64 v[20:21], 6, v[214:215]
	v_lshl_add_u64 v[20:21], s[38:39], 0, v[20:21]
	v_lshl_add_u64 v[20:21], s[82:83], 2, v[20:21]
	s_lshl_b32 s76, s55, 2
	v_lshl_add_u64 v[20:21], v[20:21], 0, s[76:77]
	s_waitcnt lgkmcnt(0)
	v_add_f32_e32 v18, v18, v19
	global_store_dword v[20:21], v18, off
.LBB0_288:
	s_or_b64 exec, exec, s[48:49]
	s_waitcnt vmcnt(22)
	v_lshlrev_b32_e32 v18, 16, v106
	s_waitcnt lgkmcnt(0)
	v_and_b32_e32 v19, 0xffff0000, v106
	v_pk_fma_f32 v[14:15], v[14:15], 0.5, v[18:19] op_sel_hi:[1,0,1]
	v_lshlrev_b32_e32 v18, 16, v107
	v_and_b32_e32 v19, 0xffff0000, v107
	v_pk_fma_f32 v[16:17], v[16:17], 0.5, v[18:19] op_sel_hi:[1,0,1]
	v_lshlrev_b32_e32 v18, 16, v108
	v_and_b32_e32 v19, 0xffff0000, v108
	v_pk_fma_f32 v[10:11], v[10:11], 0.5, v[18:19] op_sel_hi:[1,0,1]
	v_pk_add_f32 v[14:15], v[14:15], 0 op_sel_hi:[1,0]
	v_pk_add_f32 v[18:19], v[10:11], 0 op_sel_hi:[1,0]
	v_lshlrev_b32_e32 v10, 16, v109
	v_and_b32_e32 v11, 0xffff0000, v109
	v_pk_fma_f32 v[10:11], v[12:13], 0.5, v[10:11] op_sel_hi:[1,0,1]
	v_pk_add_f32 v[16:17], v[16:17], 0 op_sel_hi:[1,0]
	v_pk_add_f32 v[20:21], v[10:11], 0 op_sel_hi:[1,0]
	v_cvt_pk_bf16_f32 v10, v14, v15
	v_cvt_pk_bf16_f32 v11, v16, v17
	v_and_b32_e32 v15, 0xffff0000, v10
	v_lshlrev_b32_e32 v14, 16, v10
	v_and_b32_e32 v17, 0xffff0000, v11
	v_mul_f32_e32 v15, v15, v15
	v_cvt_pk_bf16_f32 v12, v18, v19
	v_lshlrev_b32_e32 v16, 16, v11
	v_fmac_f32_e32 v15, v14, v14
	v_mul_f32_e32 v14, v17, v17
	v_and_b32_e32 v19, 0xffff0000, v12
	v_fmac_f32_e32 v14, v16, v16
	v_cvt_pk_bf16_f32 v13, v20, v21
	v_lshlrev_b32_e32 v18, 16, v12
	v_add_f32_e32 v14, v15, v14
	v_mul_f32_e32 v15, v19, v19
	v_and_b32_e32 v21, 0xffff0000, v13
	v_fmac_f32_e32 v15, v18, v18
	v_lshlrev_b32_e32 v20, 16, v13
	v_add_f32_e32 v14, v15, v14
	v_mul_f32_e32 v15, v21, v21
	v_fmac_f32_e32 v15, v20, v20
	v_add_f32_e32 v16, v15, v14
	s_waitcnt vmcnt(21)
	v_lshlrev_b32_e32 v14, 16, v94
	v_and_b32_e32 v15, 0xffff0000, v94
	v_pk_fma_f32 v[6:7], v[6:7], 0.5, v[14:15] op_sel_hi:[1,0,1]
	v_lshlrev_b32_e32 v14, 16, v95
	v_and_b32_e32 v15, 0xffff0000, v95
	v_pk_fma_f32 v[8:9], v[8:9], 0.5, v[14:15] op_sel_hi:[1,0,1]
	v_lshlrev_b32_e32 v14, 16, v96
	v_and_b32_e32 v15, 0xffff0000, v96
	v_pk_fma_f32 v[2:3], v[2:3], 0.5, v[14:15] op_sel_hi:[1,0,1]
	v_lshlrev_b32_e32 v14, 16, v97
	v_and_b32_e32 v15, 0xffff0000, v97
	v_pk_add_f32 v[6:7], v[6:7], 0 op_sel_hi:[1,0]
	v_pk_fma_f32 v[4:5], v[4:5], 0.5, v[14:15] op_sel_hi:[1,0,1]
	v_pk_add_f32 v[2:3], v[2:3], 0 op_sel_hi:[1,0]
	v_pk_add_f32 v[14:15], v[4:5], 0 op_sel_hi:[1,0]
	v_cvt_pk_bf16_f32 v4, v6, v7
	v_pk_add_f32 v[8:9], v[8:9], 0 op_sel_hi:[1,0]
	v_cvt_pk_bf16_f32 v6, v2, v3
	v_and_b32_e32 v3, 0xffff0000, v4
	v_cvt_pk_bf16_f32 v5, v8, v9
	v_lshlrev_b32_e32 v2, 16, v4
	v_mul_f32_e32 v3, v3, v3
	v_and_b32_e32 v9, 0xffff0000, v5
	v_fmac_f32_e32 v3, v2, v2
	v_lshlrev_b32_e32 v8, 16, v5
	v_add_f32_e32 v2, v3, v16
	v_mul_f32_e32 v3, v9, v9
	v_cvt_pk_bf16_f32 v7, v14, v15
	v_and_b32_e32 v15, 0xffff0000, v6
	v_fmac_f32_e32 v3, v8, v8
	v_lshlrev_b32_e32 v14, 16, v6
	v_add_f32_e32 v2, v3, v2
	v_mul_f32_e32 v3, v15, v15
	v_and_b32_e32 v18, 0xffff0000, v7
	v_fmac_f32_e32 v3, v14, v14
	v_lshlrev_b32_e32 v17, 16, v7
	v_add_f32_e32 v2, v3, v2
	v_mul_f32_e32 v3, v18, v18
	v_fmac_f32_e32 v3, v17, v17
	v_add_f32_e32 v2, v3, v2
	v_mov_b32_e32 v3, v2
	s_nop 1
	v_permlane16_swap_b32_e32 v3, v2
	v_lshl_add_u64 v[8:9], s[88:89], 0, v[208:209]
	v_lshl_add_u64 v[8:9], v[204:205], 1, v[8:9]
	global_store_dwordx4 v[8:9], v[10:13], off
	global_store_dwordx4 v[8:9], v[4:7], off offset:256
	s_waitcnt lgkmcnt(0)
	v_add_f32_e32 v2, v2, v3
	v_mov_b32_e32 v3, v2
	s_nop 1
	v_permlane32_swap_b32_e32 v3, v2
	s_and_saveexec_b64 s[48:49], vcc
	s_cbranch_execz .LBB0_290
	v_lshlrev_b64 v[4:5], 6, v[206:207]
	v_lshl_add_u64 v[4:5], s[38:39], 0, v[4:5]
	v_lshl_add_u64 v[4:5], s[82:83], 2, v[4:5]
	s_lshl_b32 s76, s55, 2
	v_lshl_add_u64 v[4:5], v[4:5], 0, s[76:77]
	s_waitcnt lgkmcnt(0)
	v_add_f32_e32 v2, v2, v3
	global_store_dword v[4:5], v2, off

.LBB0_831:
	s_lshl_b32 s9, s21, 8
	s_add_i32 s9, s9, s55
	v_and_or_b32 v228, v124, 15, s9
	v_lshlrev_b64 v[232:233], 1, v[224:225]
	v_ashrrev_i32_e32 v229, 31, v228
	v_lshl_add_u64 v[122:123], s[88:89], 0, v[232:233]
	v_lshlrev_b64 v[236:237], 11, v[228:229]
	v_lshlrev_b32_e32 v212, 2, v124
	v_cmp_gt_u32_e32 vcc, 16, v124
	v_lshl_add_u64 v[124:125], v[122:123], 0, v[236:237]
	global_load_dwordx4 v[206:209], v[124:125], off
	global_load_dwordx4 v[202:205], v[124:125], off offset:256
	v_or_b32_e32 v210, 16, v228
	v_ashrrev_i32_e32 v211, 31, v210
	v_lshlrev_b64 v[124:125], 11, v[210:211]
	v_or_b32_e32 v246, 32, v228
	v_lshl_add_u64 v[124:125], v[122:123], 0, v[124:125]
	v_ashrrev_i32_e32 v247, 31, v246
	global_load_dwordx4 v[198:201], v[124:125], off
	global_load_dwordx4 v[194:197], v[124:125], off offset:256
	v_lshlrev_b64 v[124:125], 11, v[246:247]
	v_or_b32_e32 v242, 48, v228
	v_lshl_add_u64 v[124:125], v[122:123], 0, v[124:125]
	v_ashrrev_i32_e32 v243, 31, v242
	global_load_dwordx4 v[190:193], v[124:125], off
	global_load_dwordx4 v[186:189], v[124:125], off offset:256
	v_lshlrev_b64 v[124:125], 11, v[242:243]
	v_add_u32_e32 v238, 0x80, v228
	v_lshl_add_u64 v[124:125], v[122:123], 0, v[124:125]
	v_ashrrev_i32_e32 v239, 31, v238
	global_load_dwordx4 v[182:185], v[124:125], off
	global_load_dwordx4 v[178:181], v[124:125], off offset:256
	v_lshlrev_b64 v[124:125], 11, v[238:239]
	v_add_u32_e32 v234, 0x90, v228
	v_lshl_add_u64 v[124:125], v[122:123], 0, v[124:125]
	v_ashrrev_i32_e32 v235, 31, v234
	global_load_dwordx4 v[166:169], v[124:125], off
	global_load_dwordx4 v[162:165], v[124:125], off offset:256
	v_lshlrev_b64 v[124:125], 11, v[234:235]
	v_add_u32_e32 v230, 0xa0, v228
	v_lshl_add_u64 v[124:125], v[122:123], 0, v[124:125]
	v_ashrrev_i32_e32 v231, 31, v230
	global_load_dwordx4 v[158:161], v[124:125], off
	global_load_dwordx4 v[154:157], v[124:125], off offset:256
	v_lshlrev_b64 v[124:125], 11, v[230:231]
	v_add_u32_e32 v226, 0xb0, v228
	v_lshl_add_u64 v[124:125], v[122:123], 0, v[124:125]
	v_ashrrev_i32_e32 v227, 31, v226
	global_load_dwordx4 v[150:153], v[124:125], off
	global_load_dwordx4 v[138:141], v[124:125], off offset:256
	v_lshlrev_b64 v[124:125], 11, v[226:227]
	v_lshl_add_u64 v[122:123], v[122:123], 0, v[124:125]
	global_load_dwordx4 v[130:133], v[122:123], off
	s_nop 0
	global_load_dwordx4 v[122:125], v[122:123], off offset:256
	v_xor_b32_e32 v249, 64, v212
	v_xor_b32_e32 v248, 0x80, v212
	s_lshl_b32 s10, s20, 2
	s_ashr_i32 s11, s10, 31
	s_waitcnt vmcnt(15)
	v_lshlrev_b32_e32 v212, 16, v206
	v_and_b32_e32 v213, 0xffff0000, v206
	v_lshlrev_b32_e32 v206, 16, v207
	v_and_b32_e32 v207, 0xffff0000, v207
	v_pk_add_f32 v[176:177], v[176:177], v[206:207]
	v_lshlrev_b32_e32 v206, 16, v208
	v_and_b32_e32 v207, 0xffff0000, v208
	v_pk_add_f32 v[174:175], v[174:175], v[212:213]
	v_pk_add_f32 v[170:171], v[170:171], v[206:207]
	v_lshlrev_b32_e32 v206, 16, v209
	v_and_b32_e32 v207, 0xffff0000, v209
	v_pk_add_f32 v[174:175], v[106:107], v[174:175]
	v_pk_add_f32 v[170:171], v[94:95], v[170:171]
	v_pk_add_f32 v[172:173], v[172:173], v[206:207]
	v_pk_add_f32 v[176:177], v[108:109], v[176:177]
	v_pk_add_f32 v[206:207], v[96:97], v[172:173]
	v_cvt_pk_bf16_f32 v172, v174, v175
	v_cvt_pk_bf16_f32 v174, v170, v171
	v_lshl_add_u64 v[170:171], s[88:89], 0, v[236:237]
	v_cvt_pk_bf16_f32 v173, v176, v177
	v_cvt_pk_bf16_f32 v175, v206, v207
	v_lshl_add_u64 v[170:171], v[170:171], 0, v[232:233]
	global_store_dwordx4 v[170:171], v[172:175], off
	v_lshlrev_b32_e32 v176, 16, v172
	v_lshlrev_b32_e32 v177, 16, v173
	v_and_b32_e32 v172, 0xffff0000, v172
	v_and_b32_e32 v173, 0xffff0000, v173
	v_mul_f32_e32 v172, v172, v172
	v_mul_f32_e32 v173, v173, v173
	v_lshlrev_b32_e32 v206, 16, v174
	v_and_b32_e32 v174, 0xffff0000, v174
	v_fmac_f32_e32 v172, v176, v176
	v_fmac_f32_e32 v173, v177, v177
	v_add_f32_e32 v172, v172, v173
	v_mul_f32_e32 v173, v174, v174
	v_lshlrev_b32_e32 v207, 16, v175
	v_and_b32_e32 v175, 0xffff0000, v175
	v_fmac_f32_e32 v173, v206, v206
	v_add_f32_e32 v172, v173, v172
	v_mul_f32_e32 v173, v175, v175
	v_fmac_f32_e32 v173, v207, v207
	v_add_f32_e32 v176, v173, v172
	s_waitcnt vmcnt(15)
	v_lshlrev_b32_e32 v172, 16, v202
	v_and_b32_e32 v173, 0xffff0000, v202
	v_pk_add_f32 v[146:147], v[146:147], v[172:173]
	v_lshlrev_b32_e32 v172, 16, v203
	v_and_b32_e32 v173, 0xffff0000, v203
	v_pk_add_f32 v[148:149], v[148:149], v[172:173]
	v_lshlrev_b32_e32 v172, 16, v204
	v_and_b32_e32 v173, 0xffff0000, v204
	v_pk_add_f32 v[142:143], v[142:143], v[172:173]
	v_pk_add_f32 v[146:147], v[102:103], v[146:147]
	v_pk_add_f32 v[172:173], v[90:91], v[142:143]
	v_lshlrev_b32_e32 v142, 16, v205
	v_and_b32_e32 v143, 0xffff0000, v205
	v_pk_add_f32 v[142:143], v[144:145], v[142:143]
	v_pk_add_f32 v[148:149], v[104:105], v[148:149]
	v_pk_add_f32 v[174:175], v[92:93], v[142:143]
	v_cvt_pk_bf16_f32 v142, v146, v147
	v_cvt_pk_bf16_f32 v143, v148, v149
	v_cvt_pk_bf16_f32 v144, v172, v173
	v_cvt_pk_bf16_f32 v145, v174, v175
	global_store_dwordx4 v[170:171], v[142:145], off offset:256
	v_lshlrev_b32_e32 v146, 16, v142
	v_lshlrev_b32_e32 v147, 16, v143
	v_and_b32_e32 v142, 0xffff0000, v142
	v_and_b32_e32 v143, 0xffff0000, v143
	v_mul_f32_e32 v142, v142, v142
	v_fmac_f32_e32 v142, v146, v146
	v_mul_f32_e32 v143, v143, v143
	v_lshlrev_b32_e32 v148, 16, v144
	v_and_b32_e32 v144, 0xffff0000, v144
	v_add_f32_e32 v142, v142, v176
	v_fmac_f32_e32 v143, v147, v147
	v_add_f32_e32 v142, v143, v142
	v_mul_f32_e32 v143, v144, v144
	v_lshlrev_b32_e32 v149, 16, v145
	v_and_b32_e32 v145, 0xffff0000, v145
	v_fmac_f32_e32 v143, v148, v148
	v_add_f32_e32 v142, v143, v142
	v_mul_f32_e32 v143, v145, v145
	v_fmac_f32_e32 v143, v149, v149
	v_add_f32_e32 v142, v143, v142
	v_mov_b32_e32 v143, v142
	s_nop 1
	v_permlane16_swap_b32_e32 v143, v142
	s_waitcnt lgkmcnt(0)
	v_add_f32_e32 v142, v142, v143
	v_mov_b32_e32 v143, v142
	s_nop 1
	v_permlane32_swap_b32_e32 v143, v142
	s_and_saveexec_b64 s[42:43], vcc
	s_cbranch_execz .LBB0_833
	v_lshlrev_b64 v[144:145], 6, v[228:229]
	v_lshl_add_u64 v[144:145], s[68:69], 0, v[144:145]
	v_lshl_add_u64 v[144:145], s[10:11], 2, v[144:145]
	s_lshl_b32 s76, s54, 2
	v_lshl_add_u64 v[144:145], v[144:145], 0, s[76:77]
	s_waitcnt lgkmcnt(0)
	v_add_f32_e32 v142, v142, v143
	global_store_dword v[144:145], v142, off
.LBB0_833:
	s_or_b64 exec, exec, s[42:43]
	s_waitcnt vmcnt(16)
	v_lshlrev_b32_e32 v142, 16, v198
	s_waitcnt lgkmcnt(0)
	v_and_b32_e32 v143, 0xffff0000, v198
	v_pk_add_f32 v[134:135], v[134:135], v[142:143]
	v_lshlrev_b32_e32 v142, 16, v199
	v_and_b32_e32 v143, 0xffff0000, v199
	v_pk_add_f32 v[136:137], v[136:137], v[142:143]
	v_lshlrev_b32_e32 v142, 16, v200
	v_and_b32_e32 v143, 0xffff0000, v200
	v_pk_add_f32 v[126:127], v[126:127], v[142:143]
	v_pk_add_f32 v[134:135], v[106:107], v[134:135]
	v_pk_add_f32 v[142:143], v[94:95], v[126:127]
	v_lshlrev_b32_e32 v126, 16, v201
	v_and_b32_e32 v127, 0xffff0000, v201
	v_pk_add_f32 v[126:127], v[128:129], v[126:127]
	v_pk_add_f32 v[136:137], v[108:109], v[136:137]
	v_pk_add_f32 v[144:145], v[96:97], v[126:127]
	v_cvt_pk_bf16_f32 v126, v134, v135
	v_cvt_pk_bf16_f32 v127, v136, v137
	v_and_b32_e32 v135, 0xffff0000, v126
	v_lshlrev_b32_e32 v134, 16, v126
	v_and_b32_e32 v137, 0xffff0000, v127
	v_mul_f32_e32 v135, v135, v135
	v_cvt_pk_bf16_f32 v128, v142, v143
	v_lshlrev_b32_e32 v136, 16, v127
	v_fmac_f32_e32 v135, v134, v134
	v_mul_f32_e32 v134, v137, v137
	v_and_b32_e32 v143, 0xffff0000, v128
	v_fmac_f32_e32 v134, v136, v136
	v_cvt_pk_bf16_f32 v129, v144, v145
	v_lshlrev_b32_e32 v142, 16, v128
	v_add_f32_e32 v134, v135, v134
	v_mul_f32_e32 v135, v143, v143
	v_and_b32_e32 v145, 0xffff0000, v129
	v_fmac_f32_e32 v135, v142, v142
	v_lshlrev_b32_e32 v144, 16, v129
	v_add_f32_e32 v134, v135, v134
	v_mul_f32_e32 v135, v145, v145
	v_fmac_f32_e32 v135, v144, v144
	v_add_f32_e32 v136, v135, v134
	s_waitcnt vmcnt(15)
	v_lshlrev_b32_e32 v134, 16, v194
	v_and_b32_e32 v135, 0xffff0000, v194
	v_pk_add_f32 v[118:119], v[118:119], v[134:135]
	v_lshlrev_b32_e32 v134, 16, v195
	v_and_b32_e32 v135, 0xffff0000, v195
	v_pk_add_f32 v[120:121], v[120:121], v[134:135]
	v_lshlrev_b32_e32 v134, 16, v196
	v_and_b32_e32 v135, 0xffff0000, v196
	v_pk_add_f32 v[114:115], v[114:115], v[134:135]
	v_lshlrev_b32_e32 v134, 16, v197
	v_and_b32_e32 v135, 0xffff0000, v197
	v_pk_add_f32 v[118:119], v[102:103], v[118:119]
	v_pk_add_f32 v[116:117], v[116:117], v[134:135]
	v_pk_add_f32 v[114:115], v[90:91], v[114:115]
	v_pk_add_f32 v[134:135], v[92:93], v[116:117]
	v_cvt_pk_bf16_f32 v116, v118, v119
	v_pk_add_f32 v[120:121], v[104:105], v[120:121]
	v_cvt_pk_bf16_f32 v118, v114, v115
	v_and_b32_e32 v115, 0xffff0000, v116
	v_cvt_pk_bf16_f32 v117, v120, v121
	v_lshlrev_b32_e32 v114, 16, v116
	v_mul_f32_e32 v115, v115, v115
	v_and_b32_e32 v121, 0xffff0000, v117
	v_fmac_f32_e32 v115, v114, v114
	v_lshlrev_b32_e32 v120, 16, v117
	v_add_f32_e32 v114, v115, v136
	v_mul_f32_e32 v115, v121, v121
	v_cvt_pk_bf16_f32 v119, v134, v135
	v_and_b32_e32 v135, 0xffff0000, v118
	v_fmac_f32_e32 v115, v120, v120
	v_lshlrev_b32_e32 v134, 16, v118
	v_add_f32_e32 v114, v115, v114
	v_mul_f32_e32 v115, v135, v135
	v_and_b32_e32 v142, 0xffff0000, v119
	v_fmac_f32_e32 v115, v134, v134
	v_lshlrev_b32_e32 v137, 16, v119
	v_add_f32_e32 v114, v115, v114
	v_mul_f32_e32 v115, v142, v142
	v_fmac_f32_e32 v115, v137, v137
	v_add_f32_e32 v114, v115, v114
	v_mov_b32_e32 v115, v114
	s_nop 1
	v_permlane16_swap_b32_e32 v115, v114
	v_lshlrev_b64 v[120:121], 11, v[210:211]
	v_lshl_add_u64 v[120:121], s[88:89], 0, v[120:121]
	v_lshl_add_u64 v[120:121], v[224:225], 1, v[120:121]
	global_store_dwordx4 v[120:121], v[126:129], off
	global_store_dwordx4 v[120:121], v[116:119], off offset:256
	s_waitcnt lgkmcnt(0)
	v_add_f32_e32 v114, v114, v115
	v_mov_b32_e32 v115, v114
	s_nop 1
	v_permlane32_swap_b32_e32 v115, v114
	s_and_saveexec_b64 s[42:43], vcc
	s_cbranch_execz .LBB0_835
	v_lshlrev_b64 v[116:117], 6, v[210:211]
	v_lshl_add_u64 v[116:117], s[68:69], 0, v[116:117]
	v_lshl_add_u64 v[116:117], s[10:11], 2, v[116:117]
	s_lshl_b32 s76, s54, 2
	v_lshl_add_u64 v[116:117], v[116:117], 0, s[76:77]
	s_waitcnt lgkmcnt(0)
	v_add_f32_e32 v114, v114, v115
	global_store_dword v[116:117], v114, off
.LBB0_835:
	s_or_b64 exec, exec, s[42:43]
	s_waitcnt vmcnt(17)
	v_lshlrev_b32_e32 v114, 16, v190
	s_waitcnt lgkmcnt(0)
	v_and_b32_e32 v115, 0xffff0000, v190
	v_pk_add_f32 v[110:111], v[110:111], v[114:115]
	v_lshlrev_b32_e32 v114, 16, v191
	v_and_b32_e32 v115, 0xffff0000, v191
	v_pk_add_f32 v[112:113], v[112:113], v[114:115]
	v_lshlrev_b32_e32 v114, 16, v192
	v_and_b32_e32 v115, 0xffff0000, v192
	v_pk_add_f32 v[98:99], v[98:99], v[114:115]
	v_pk_add_f32 v[110:111], v[106:107], v[110:111]
	v_pk_add_f32 v[114:115], v[94:95], v[98:99]
	v_lshlrev_b32_e32 v98, 16, v193
	v_and_b32_e32 v99, 0xffff0000, v193
	v_pk_add_f32 v[98:99], v[100:101], v[98:99]
	v_pk_add_f32 v[112:113], v[108:109], v[112:113]
	v_pk_add_f32 v[116:117], v[96:97], v[98:99]
	v_cvt_pk_bf16_f32 v98, v110, v111
	v_cvt_pk_bf16_f32 v99, v112, v113
	v_and_b32_e32 v111, 0xffff0000, v98
	v_lshlrev_b32_e32 v110, 16, v98
	v_and_b32_e32 v113, 0xffff0000, v99
	v_mul_f32_e32 v111, v111, v111
	v_cvt_pk_bf16_f32 v100, v114, v115
	v_lshlrev_b32_e32 v112, 16, v99
	v_fmac_f32_e32 v111, v110, v110
	v_mul_f32_e32 v110, v113, v113
	v_and_b32_e32 v115, 0xffff0000, v100
	v_fmac_f32_e32 v110, v112, v112
	v_cvt_pk_bf16_f32 v101, v116, v117
	v_lshlrev_b32_e32 v114, 16, v100
	v_add_f32_e32 v110, v111, v110
	v_mul_f32_e32 v111, v115, v115
	v_and_b32_e32 v117, 0xffff0000, v101
	v_fmac_f32_e32 v111, v114, v114
	v_lshlrev_b32_e32 v116, 16, v101
	v_add_f32_e32 v110, v111, v110
	v_mul_f32_e32 v111, v117, v117
	v_fmac_f32_e32 v111, v116, v116
	v_add_f32_e32 v112, v111, v110
	s_waitcnt vmcnt(16)
	v_lshlrev_b32_e32 v110, 16, v186
	v_and_b32_e32 v111, 0xffff0000, v186
	v_pk_add_f32 v[86:87], v[86:87], v[110:111]
	v_lshlrev_b32_e32 v110, 16, v187
	v_and_b32_e32 v111, 0xffff0000, v187
	v_pk_add_f32 v[88:89], v[88:89], v[110:111]
	v_lshlrev_b32_e32 v110, 16, v188
	v_and_b32_e32 v111, 0xffff0000, v188
	v_pk_add_f32 v[82:83], v[82:83], v[110:111]
	v_lshlrev_b32_e32 v110, 16, v189
	v_and_b32_e32 v111, 0xffff0000, v189
	v_pk_add_f32 v[86:87], v[102:103], v[86:87]
	v_pk_add_f32 v[84:85], v[84:85], v[110:111]
	v_pk_add_f32 v[82:83], v[90:91], v[82:83]
	v_pk_add_f32 v[110:111], v[92:93], v[84:85]
	v_cvt_pk_bf16_f32 v84, v86, v87
	v_pk_add_f32 v[88:89], v[104:105], v[88:89]
	v_cvt_pk_bf16_f32 v86, v82, v83
	v_and_b32_e32 v83, 0xffff0000, v84
	v_cvt_pk_bf16_f32 v85, v88, v89
	v_lshlrev_b32_e32 v82, 16, v84
	v_mul_f32_e32 v83, v83, v83
	v_and_b32_e32 v89, 0xffff0000, v85
	v_fmac_f32_e32 v83, v82, v82
	v_lshlrev_b32_e32 v88, 16, v85
	v_add_f32_e32 v82, v83, v112
	v_mul_f32_e32 v83, v89, v89
	v_cvt_pk_bf16_f32 v87, v110, v111
	v_and_b32_e32 v111, 0xffff0000, v86
	v_fmac_f32_e32 v83, v88, v88
	v_lshlrev_b32_e32 v110, 16, v86
	v_add_f32_e32 v82, v83, v82
	v_mul_f32_e32 v83, v111, v111
	v_and_b32_e32 v114, 0xffff0000, v87
	v_fmac_f32_e32 v83, v110, v110
	v_lshlrev_b32_e32 v113, 16, v87
	v_add_f32_e32 v82, v83, v82
	v_mul_f32_e32 v83, v114, v114
	v_fmac_f32_e32 v83, v113, v113
	v_add_f32_e32 v82, v83, v82
	v_mov_b32_e32 v83, v82
	s_nop 1
	v_permlane16_swap_b32_e32 v83, v82
	v_lshlrev_b64 v[88:89], 11, v[246:247]
	v_lshl_add_u64 v[88:89], s[88:89], 0, v[88:89]
	v_lshl_add_u64 v[88:89], v[224:225], 1, v[88:89]
	global_store_dwordx4 v[88:89], v[98:101], off
	global_store_dwordx4 v[88:89], v[84:87], off offset:256
	s_waitcnt lgkmcnt(0)
	v_add_f32_e32 v82, v82, v83
	v_mov_b32_e32 v83, v82
	s_nop 1
	v_permlane32_swap_b32_e32 v83, v82
	s_and_saveexec_b64 s[42:43], vcc
	s_cbranch_execz .LBB0_837
	v_lshlrev_b64 v[84:85], 6, v[246:247]
	v_lshl_add_u64 v[84:85], s[68:69], 0, v[84:85]
	v_lshl_add_u64 v[84:85], s[10:11], 2, v[84:85]
	s_lshl_b32 s76, s54, 2
	v_lshl_add_u64 v[84:85], v[84:85], 0, s[76:77]
	s_waitcnt lgkmcnt(0)
	v_add_f32_e32 v82, v82, v83
	global_store_dword v[84:85], v82, off
.LBB0_837:
	s_or_b64 exec, exec, s[42:43]
	s_waitcnt vmcnt(18)
	v_lshlrev_b32_e32 v82, 16, v182
	s_waitcnt lgkmcnt(0)
	v_and_b32_e32 v83, 0xffff0000, v182
	v_pk_add_f32 v[78:79], v[78:79], v[82:83]
	v_lshlrev_b32_e32 v82, 16, v183
	v_and_b32_e32 v83, 0xffff0000, v183
	v_pk_add_f32 v[80:81], v[80:81], v[82:83]
	v_lshlrev_b32_e32 v82, 16, v184
	v_and_b32_e32 v83, 0xffff0000, v184
	v_pk_add_f32 v[74:75], v[74:75], v[82:83]
	v_pk_add_f32 v[78:79], v[106:107], v[78:79]
	v_pk_add_f32 v[82:83], v[94:95], v[74:75]
	v_lshlrev_b32_e32 v74, 16, v185
	v_and_b32_e32 v75, 0xffff0000, v185
	v_pk_add_f32 v[74:75], v[76:77], v[74:75]
	v_pk_add_f32 v[80:81], v[108:109], v[80:81]
	v_pk_add_f32 v[84:85], v[96:97], v[74:75]
	v_cvt_pk_bf16_f32 v74, v78, v79
	v_cvt_pk_bf16_f32 v75, v80, v81
	v_and_b32_e32 v79, 0xffff0000, v74
	v_lshlrev_b32_e32 v78, 16, v74
	v_and_b32_e32 v81, 0xffff0000, v75
	v_mul_f32_e32 v79, v79, v79
	v_cvt_pk_bf16_f32 v76, v82, v83
	v_lshlrev_b32_e32 v80, 16, v75
	v_fmac_f32_e32 v79, v78, v78
	v_mul_f32_e32 v78, v81, v81
	v_and_b32_e32 v83, 0xffff0000, v76
	v_fmac_f32_e32 v78, v80, v80
	v_cvt_pk_bf16_f32 v77, v84, v85
	v_lshlrev_b32_e32 v82, 16, v76
	v_add_f32_e32 v78, v79, v78
	v_mul_f32_e32 v79, v83, v83
	v_and_b32_e32 v85, 0xffff0000, v77
	v_fmac_f32_e32 v79, v82, v82
	v_lshlrev_b32_e32 v84, 16, v77
	v_add_f32_e32 v78, v79, v78
	v_mul_f32_e32 v79, v85, v85
	v_fmac_f32_e32 v79, v84, v84
	v_add_f32_e32 v80, v79, v78
	s_waitcnt vmcnt(17)
	v_lshlrev_b32_e32 v78, 16, v178
	v_and_b32_e32 v79, 0xffff0000, v178
	v_pk_add_f32 v[70:71], v[70:71], v[78:79]
	v_lshlrev_b32_e32 v78, 16, v179
	v_and_b32_e32 v79, 0xffff0000, v179
	v_pk_add_f32 v[72:73], v[72:73], v[78:79]
	v_lshlrev_b32_e32 v78, 16, v180
	v_and_b32_e32 v79, 0xffff0000, v180
	v_pk_add_f32 v[66:67], v[66:67], v[78:79]
	v_lshlrev_b32_e32 v78, 16, v181
	v_and_b32_e32 v79, 0xffff0000, v181
	v_pk_add_f32 v[70:71], v[102:103], v[70:71]
	v_pk_add_f32 v[68:69], v[68:69], v[78:79]
	v_pk_add_f32 v[66:67], v[90:91], v[66:67]
	v_pk_add_f32 v[78:79], v[92:93], v[68:69]
	v_cvt_pk_bf16_f32 v68, v70, v71
	v_pk_add_f32 v[72:73], v[104:105], v[72:73]
	v_cvt_pk_bf16_f32 v70, v66, v67
	v_and_b32_e32 v67, 0xffff0000, v68
	v_cvt_pk_bf16_f32 v69, v72, v73
	v_lshlrev_b32_e32 v66, 16, v68
	v_mul_f32_e32 v67, v67, v67
	v_and_b32_e32 v73, 0xffff0000, v69
	v_fmac_f32_e32 v67, v66, v66
	v_lshlrev_b32_e32 v72, 16, v69
	v_add_f32_e32 v66, v67, v80
	v_mul_f32_e32 v67, v73, v73
	v_cvt_pk_bf16_f32 v71, v78, v79
	v_and_b32_e32 v79, 0xffff0000, v70
	v_fmac_f32_e32 v67, v72, v72
	v_lshlrev_b32_e32 v78, 16, v70
	v_add_f32_e32 v66, v67, v66
	v_mul_f32_e32 v67, v79, v79
	v_and_b32_e32 v82, 0xffff0000, v71
	v_fmac_f32_e32 v67, v78, v78
	v_lshlrev_b32_e32 v81, 16, v71
	v_add_f32_e32 v66, v67, v66
	v_mul_f32_e32 v67, v82, v82
	v_fmac_f32_e32 v67, v81, v81
	v_add_f32_e32 v66, v67, v66
	v_mov_b32_e32 v67, v66
	s_nop 1
	v_permlane16_swap_b32_e32 v67, v66
	v_lshlrev_b64 v[72:73], 11, v[242:243]
	v_lshl_add_u64 v[72:73], s[88:89], 0, v[72:73]
	v_lshl_add_u64 v[72:73], v[224:225], 1, v[72:73]
	global_store_dwordx4 v[72:73], v[74:77], off
	global_store_dwordx4 v[72:73], v[68:71], off offset:256
	s_waitcnt lgkmcnt(0)
	v_add_f32_e32 v66, v66, v67
	v_mov_b32_e32 v67, v66
	s_nop 1
	v_permlane32_swap_b32_e32 v67, v66
	s_and_saveexec_b64 s[42:43], vcc
	s_cbranch_execz .LBB0_839
	v_lshlrev_b64 v[68:69], 6, v[242:243]
	v_lshl_add_u64 v[68:69], s[68:69], 0, v[68:69]
	v_lshl_add_u64 v[68:69], s[10:11], 2, v[68:69]
	s_lshl_b32 s76, s54, 2
	v_lshl_add_u64 v[68:69], v[68:69], 0, s[76:77]
	s_waitcnt lgkmcnt(0)
	v_add_f32_e32 v66, v66, v67
	global_store_dword v[68:69], v66, off
.LBB0_839:
	s_or_b64 exec, exec, s[42:43]
	s_waitcnt vmcnt(19)
	v_lshlrev_b32_e32 v66, 16, v166
	s_waitcnt lgkmcnt(0)
	v_and_b32_e32 v67, 0xffff0000, v166
	v_pk_add_f32 v[62:63], v[62:63], v[66:67]
	v_lshlrev_b32_e32 v66, 16, v167
	v_and_b32_e32 v67, 0xffff0000, v167
	v_pk_add_f32 v[64:65], v[64:65], v[66:67]
	v_lshlrev_b32_e32 v66, 16, v168
	v_and_b32_e32 v67, 0xffff0000, v168
	v_pk_add_f32 v[58:59], v[58:59], v[66:67]
	v_pk_add_f32 v[62:63], v[106:107], v[62:63]
	v_pk_add_f32 v[66:67], v[94:95], v[58:59]
	v_lshlrev_b32_e32 v58, 16, v169
	v_and_b32_e32 v59, 0xffff0000, v169
	v_pk_add_f32 v[58:59], v[60:61], v[58:59]
	v_pk_add_f32 v[64:65], v[108:109], v[64:65]
	v_pk_add_f32 v[68:69], v[96:97], v[58:59]
	v_cvt_pk_bf16_f32 v58, v62, v63
	v_cvt_pk_bf16_f32 v59, v64, v65
	v_and_b32_e32 v63, 0xffff0000, v58
	v_lshlrev_b32_e32 v62, 16, v58
	v_and_b32_e32 v65, 0xffff0000, v59
	v_mul_f32_e32 v63, v63, v63
	v_cvt_pk_bf16_f32 v60, v66, v67
	v_lshlrev_b32_e32 v64, 16, v59
	v_fmac_f32_e32 v63, v62, v62
	v_mul_f32_e32 v62, v65, v65
	v_and_b32_e32 v67, 0xffff0000, v60
	v_fmac_f32_e32 v62, v64, v64
	v_cvt_pk_bf16_f32 v61, v68, v69
	v_lshlrev_b32_e32 v66, 16, v60
	v_add_f32_e32 v62, v63, v62
	v_mul_f32_e32 v63, v67, v67
	v_and_b32_e32 v69, 0xffff0000, v61
	v_fmac_f32_e32 v63, v66, v66
	v_lshlrev_b32_e32 v68, 16, v61
	v_add_f32_e32 v62, v63, v62
	v_mul_f32_e32 v63, v69, v69
	v_fmac_f32_e32 v63, v68, v68
	v_add_f32_e32 v64, v63, v62
	s_waitcnt vmcnt(18)
	v_lshlrev_b32_e32 v62, 16, v162
	v_and_b32_e32 v63, 0xffff0000, v162
	v_pk_add_f32 v[54:55], v[54:55], v[62:63]
	v_lshlrev_b32_e32 v62, 16, v163
	v_and_b32_e32 v63, 0xffff0000, v163
	v_pk_add_f32 v[56:57], v[56:57], v[62:63]
	v_lshlrev_b32_e32 v62, 16, v164
	v_and_b32_e32 v63, 0xffff0000, v164
	v_pk_add_f32 v[50:51], v[50:51], v[62:63]
	v_lshlrev_b32_e32 v62, 16, v165
	v_and_b32_e32 v63, 0xffff0000, v165
	v_pk_add_f32 v[54:55], v[102:103], v[54:55]
	v_pk_add_f32 v[52:53], v[52:53], v[62:63]
	v_pk_add_f32 v[50:51], v[90:91], v[50:51]
	v_pk_add_f32 v[62:63], v[92:93], v[52:53]
	v_cvt_pk_bf16_f32 v52, v54, v55
	v_pk_add_f32 v[56:57], v[104:105], v[56:57]
	v_cvt_pk_bf16_f32 v54, v50, v51
	v_and_b32_e32 v51, 0xffff0000, v52
	v_cvt_pk_bf16_f32 v53, v56, v57
	v_lshlrev_b32_e32 v50, 16, v52
	v_mul_f32_e32 v51, v51, v51
	v_and_b32_e32 v57, 0xffff0000, v53
	v_fmac_f32_e32 v51, v50, v50
	v_lshlrev_b32_e32 v56, 16, v53
	v_add_f32_e32 v50, v51, v64
	v_mul_f32_e32 v51, v57, v57
	v_cvt_pk_bf16_f32 v55, v62, v63
	v_and_b32_e32 v63, 0xffff0000, v54
	v_fmac_f32_e32 v51, v56, v56
	v_lshlrev_b32_e32 v62, 16, v54
	v_add_f32_e32 v50, v51, v50
	v_mul_f32_e32 v51, v63, v63
	v_and_b32_e32 v66, 0xffff0000, v55
	v_fmac_f32_e32 v51, v62, v62
	v_lshlrev_b32_e32 v65, 16, v55
	v_add_f32_e32 v50, v51, v50
	v_mul_f32_e32 v51, v66, v66
	v_fmac_f32_e32 v51, v65, v65
	v_add_f32_e32 v50, v51, v50
	v_mov_b32_e32 v51, v50
	s_nop 1
	v_permlane16_swap_b32_e32 v51, v50
	v_lshlrev_b64 v[56:57], 11, v[238:239]
	v_lshl_add_u64 v[56:57], s[88:89], 0, v[56:57]
	v_lshl_add_u64 v[56:57], v[224:225], 1, v[56:57]
	global_store_dwordx4 v[56:57], v[58:61], off
	global_store_dwordx4 v[56:57], v[52:55], off offset:256
	s_waitcnt lgkmcnt(0)
	v_add_f32_e32 v50, v50, v51
	v_mov_b32_e32 v51, v50
	s_nop 1
	v_permlane32_swap_b32_e32 v51, v50
	s_and_saveexec_b64 s[42:43], vcc
	s_cbranch_execz .LBB0_841
	v_lshlrev_b64 v[52:53], 6, v[238:239]
	v_lshl_add_u64 v[52:53], s[68:69], 0, v[52:53]
	v_lshl_add_u64 v[52:53], s[10:11], 2, v[52:53]
	s_lshl_b32 s76, s54, 2
	v_lshl_add_u64 v[52:53], v[52:53], 0, s[76:77]
	s_waitcnt lgkmcnt(0)
	v_add_f32_e32 v50, v50, v51
	global_store_dword v[52:53], v50, off
.LBB0_841:
	s_or_b64 exec, exec, s[42:43]
	s_waitcnt vmcnt(20)
	v_lshlrev_b32_e32 v50, 16, v158
	s_waitcnt lgkmcnt(0)
	v_and_b32_e32 v51, 0xffff0000, v158
	v_pk_add_f32 v[46:47], v[46:47], v[50:51]
	v_lshlrev_b32_e32 v50, 16, v159
	v_and_b32_e32 v51, 0xffff0000, v159
	v_pk_add_f32 v[48:49], v[48:49], v[50:51]
	v_lshlrev_b32_e32 v50, 16, v160
	v_and_b32_e32 v51, 0xffff0000, v160
	v_pk_add_f32 v[42:43], v[42:43], v[50:51]
	v_pk_add_f32 v[46:47], v[106:107], v[46:47]
	v_pk_add_f32 v[50:51], v[94:95], v[42:43]
	v_lshlrev_b32_e32 v42, 16, v161
	v_and_b32_e32 v43, 0xffff0000, v161
	v_pk_add_f32 v[42:43], v[44:45], v[42:43]
	v_pk_add_f32 v[48:49], v[108:109], v[48:49]
	v_pk_add_f32 v[52:53], v[96:97], v[42:43]
	v_cvt_pk_bf16_f32 v42, v46, v47
	v_cvt_pk_bf16_f32 v43, v48, v49
	v_and_b32_e32 v47, 0xffff0000, v42
	v_lshlrev_b32_e32 v46, 16, v42
	v_and_b32_e32 v49, 0xffff0000, v43
	v_mul_f32_e32 v47, v47, v47
	v_cvt_pk_bf16_f32 v44, v50, v51
	v_lshlrev_b32_e32 v48, 16, v43
	v_fmac_f32_e32 v47, v46, v46
	v_mul_f32_e32 v46, v49, v49
	v_and_b32_e32 v51, 0xffff0000, v44
	v_fmac_f32_e32 v46, v48, v48
	v_cvt_pk_bf16_f32 v45, v52, v53
	v_lshlrev_b32_e32 v50, 16, v44
	v_add_f32_e32 v46, v47, v46
	v_mul_f32_e32 v47, v51, v51
	v_and_b32_e32 v53, 0xffff0000, v45
	v_fmac_f32_e32 v47, v50, v50
	v_lshlrev_b32_e32 v52, 16, v45
	v_add_f32_e32 v46, v47, v46
	v_mul_f32_e32 v47, v53, v53
	v_fmac_f32_e32 v47, v52, v52
	v_add_f32_e32 v48, v47, v46
	s_waitcnt vmcnt(19)
	v_lshlrev_b32_e32 v46, 16, v154
	v_and_b32_e32 v47, 0xffff0000, v154
	v_pk_add_f32 v[38:39], v[38:39], v[46:47]
	v_lshlrev_b32_e32 v46, 16, v155
	v_and_b32_e32 v47, 0xffff0000, v155
	v_pk_add_f32 v[40:41], v[40:41], v[46:47]
	v_lshlrev_b32_e32 v46, 16, v156
	v_and_b32_e32 v47, 0xffff0000, v156
	v_pk_add_f32 v[34:35], v[34:35], v[46:47]
	v_lshlrev_b32_e32 v46, 16, v157
	v_and_b32_e32 v47, 0xffff0000, v157
	v_pk_add_f32 v[38:39], v[102:103], v[38:39]
	v_pk_add_f32 v[36:37], v[36:37], v[46:47]
	v_pk_add_f32 v[34:35], v[90:91], v[34:35]
	v_pk_add_f32 v[46:47], v[92:93], v[36:37]
	v_cvt_pk_bf16_f32 v36, v38, v39
	v_pk_add_f32 v[40:41], v[104:105], v[40:41]
	v_cvt_pk_bf16_f32 v38, v34, v35
	v_and_b32_e32 v35, 0xffff0000, v36
	v_cvt_pk_bf16_f32 v37, v40, v41
	v_lshlrev_b32_e32 v34, 16, v36
	v_mul_f32_e32 v35, v35, v35
	v_and_b32_e32 v41, 0xffff0000, v37
	v_fmac_f32_e32 v35, v34, v34
	v_lshlrev_b32_e32 v40, 16, v37
	v_add_f32_e32 v34, v35, v48
	v_mul_f32_e32 v35, v41, v41
	v_cvt_pk_bf16_f32 v39, v46, v47
	v_and_b32_e32 v47, 0xffff0000, v38
	v_fmac_f32_e32 v35, v40, v40
	v_lshlrev_b32_e32 v46, 16, v38
	v_add_f32_e32 v34, v35, v34
	v_mul_f32_e32 v35, v47, v47
	v_and_b32_e32 v50, 0xffff0000, v39
	v_fmac_f32_e32 v35, v46, v46
	v_lshlrev_b32_e32 v49, 16, v39
	v_add_f32_e32 v34, v35, v34
	v_mul_f32_e32 v35, v50, v50
	v_fmac_f32_e32 v35, v49, v49
	v_add_f32_e32 v34, v35, v34
	v_mov_b32_e32 v35, v34
	s_nop 1
	v_permlane16_swap_b32_e32 v35, v34
	v_lshlrev_b64 v[40:41], 11, v[234:235]
	v_lshl_add_u64 v[40:41], s[88:89], 0, v[40:41]
	v_lshl_add_u64 v[40:41], v[224:225], 1, v[40:41]
	global_store_dwordx4 v[40:41], v[42:45], off
	global_store_dwordx4 v[40:41], v[36:39], off offset:256
	s_waitcnt lgkmcnt(0)
	v_add_f32_e32 v34, v34, v35
	v_mov_b32_e32 v35, v34
	s_nop 1
	v_permlane32_swap_b32_e32 v35, v34
	s_and_saveexec_b64 s[42:43], vcc
	s_cbranch_execz .LBB0_843
	v_lshlrev_b64 v[36:37], 6, v[234:235]
	v_lshl_add_u64 v[36:37], s[68:69], 0, v[36:37]
	v_lshl_add_u64 v[36:37], s[10:11], 2, v[36:37]
	s_lshl_b32 s76, s54, 2
	v_lshl_add_u64 v[36:37], v[36:37], 0, s[76:77]
	s_waitcnt lgkmcnt(0)
	v_add_f32_e32 v34, v34, v35
	global_store_dword v[36:37], v34, off
.LBB0_843:
	s_or_b64 exec, exec, s[42:43]
	s_waitcnt vmcnt(21)
	v_lshlrev_b32_e32 v34, 16, v150
	s_waitcnt lgkmcnt(0)
	v_and_b32_e32 v35, 0xffff0000, v150
	v_pk_add_f32 v[30:31], v[30:31], v[34:35]
	v_lshlrev_b32_e32 v34, 16, v151
	v_and_b32_e32 v35, 0xffff0000, v151
	v_pk_add_f32 v[32:33], v[32:33], v[34:35]
	v_lshlrev_b32_e32 v34, 16, v152
	v_and_b32_e32 v35, 0xffff0000, v152
	v_pk_add_f32 v[26:27], v[26:27], v[34:35]
	v_pk_add_f32 v[30:31], v[106:107], v[30:31]
	v_pk_add_f32 v[34:35], v[94:95], v[26:27]
	v_lshlrev_b32_e32 v26, 16, v153
	v_and_b32_e32 v27, 0xffff0000, v153
	v_pk_add_f32 v[26:27], v[28:29], v[26:27]
	v_pk_add_f32 v[32:33], v[108:109], v[32:33]
	v_pk_add_f32 v[36:37], v[96:97], v[26:27]
	v_cvt_pk_bf16_f32 v26, v30, v31
	v_cvt_pk_bf16_f32 v27, v32, v33
	v_and_b32_e32 v31, 0xffff0000, v26
	v_lshlrev_b32_e32 v30, 16, v26
	v_and_b32_e32 v33, 0xffff0000, v27
	v_mul_f32_e32 v31, v31, v31
	v_cvt_pk_bf16_f32 v28, v34, v35
	v_lshlrev_b32_e32 v32, 16, v27
	v_fmac_f32_e32 v31, v30, v30
	v_mul_f32_e32 v30, v33, v33
	v_and_b32_e32 v35, 0xffff0000, v28
	v_fmac_f32_e32 v30, v32, v32
	v_cvt_pk_bf16_f32 v29, v36, v37
	v_lshlrev_b32_e32 v34, 16, v28
	v_add_f32_e32 v30, v31, v30
	v_mul_f32_e32 v31, v35, v35
	v_and_b32_e32 v37, 0xffff0000, v29
	v_fmac_f32_e32 v31, v34, v34
	v_lshlrev_b32_e32 v36, 16, v29
	v_add_f32_e32 v30, v31, v30
	v_mul_f32_e32 v31, v37, v37
	v_fmac_f32_e32 v31, v36, v36
	v_add_f32_e32 v32, v31, v30
	s_waitcnt vmcnt(20)
	v_lshlrev_b32_e32 v30, 16, v138
	v_and_b32_e32 v31, 0xffff0000, v138
	v_pk_add_f32 v[22:23], v[22:23], v[30:31]
	v_lshlrev_b32_e32 v30, 16, v139
	v_and_b32_e32 v31, 0xffff0000, v139
	v_pk_add_f32 v[24:25], v[24:25], v[30:31]
	v_lshlrev_b32_e32 v30, 16, v140
	v_and_b32_e32 v31, 0xffff0000, v140
	v_pk_add_f32 v[18:19], v[18:19], v[30:31]
	v_lshlrev_b32_e32 v30, 16, v141
	v_and_b32_e32 v31, 0xffff0000, v141
	v_pk_add_f32 v[22:23], v[102:103], v[22:23]
	v_pk_add_f32 v[20:21], v[20:21], v[30:31]
	v_pk_add_f32 v[18:19], v[90:91], v[18:19]
	v_pk_add_f32 v[30:31], v[92:93], v[20:21]
	v_cvt_pk_bf16_f32 v20, v22, v23
	v_pk_add_f32 v[24:25], v[104:105], v[24:25]
	v_cvt_pk_bf16_f32 v22, v18, v19
	v_and_b32_e32 v19, 0xffff0000, v20
	v_cvt_pk_bf16_f32 v21, v24, v25
	v_lshlrev_b32_e32 v18, 16, v20
	v_mul_f32_e32 v19, v19, v19
	v_and_b32_e32 v25, 0xffff0000, v21
	v_fmac_f32_e32 v19, v18, v18
	v_lshlrev_b32_e32 v24, 16, v21
	v_add_f32_e32 v18, v19, v32
	v_mul_f32_e32 v19, v25, v25
	v_cvt_pk_bf16_f32 v23, v30, v31
	v_and_b32_e32 v31, 0xffff0000, v22
	v_fmac_f32_e32 v19, v24, v24
	v_lshlrev_b32_e32 v30, 16, v22
	v_add_f32_e32 v18, v19, v18
	v_mul_f32_e32 v19, v31, v31
	v_and_b32_e32 v34, 0xffff0000, v23
	v_fmac_f32_e32 v19, v30, v30
	v_lshlrev_b32_e32 v33, 16, v23
	v_add_f32_e32 v18, v19, v18
	v_mul_f32_e32 v19, v34, v34
	v_fmac_f32_e32 v19, v33, v33
	v_add_f32_e32 v18, v19, v18
	v_mov_b32_e32 v19, v18
	s_nop 1
	v_permlane16_swap_b32_e32 v19, v18
	v_lshlrev_b64 v[24:25], 11, v[230:231]
	v_lshl_add_u64 v[24:25], s[88:89], 0, v[24:25]
	v_lshl_add_u64 v[24:25], v[224:225], 1, v[24:25]
	global_store_dwordx4 v[24:25], v[26:29], off
	global_store_dwordx4 v[24:25], v[20:23], off offset:256
	s_waitcnt lgkmcnt(0)
	v_add_f32_e32 v18, v18, v19
	v_mov_b32_e32 v19, v18
	s_nop 1
	v_permlane32_swap_b32_e32 v19, v18
	s_and_saveexec_b64 s[42:43], vcc
	s_cbranch_execz .LBB0_845
	v_lshlrev_b64 v[20:21], 6, v[230:231]
	v_lshl_add_u64 v[20:21], s[68:69], 0, v[20:21]
	v_lshl_add_u64 v[20:21], s[10:11], 2, v[20:21]
	s_lshl_b32 s76, s54, 2
	v_lshl_add_u64 v[20:21], v[20:21], 0, s[76:77]
	s_waitcnt lgkmcnt(0)
	v_add_f32_e32 v18, v18, v19
	global_store_dword v[20:21], v18, off
.LBB0_845:
	s_or_b64 exec, exec, s[42:43]
	s_waitcnt vmcnt(22)
	v_lshlrev_b32_e32 v18, 16, v130
	s_waitcnt lgkmcnt(0)
	v_and_b32_e32 v19, 0xffff0000, v130
	v_pk_add_f32 v[14:15], v[14:15], v[18:19]
	v_lshlrev_b32_e32 v18, 16, v131
	v_and_b32_e32 v19, 0xffff0000, v131
	v_pk_add_f32 v[16:17], v[16:17], v[18:19]
	v_lshlrev_b32_e32 v18, 16, v132
	v_and_b32_e32 v19, 0xffff0000, v132
	v_pk_add_f32 v[10:11], v[10:11], v[18:19]
	v_pk_add_f32 v[14:15], v[106:107], v[14:15]
	v_pk_add_f32 v[18:19], v[94:95], v[10:11]
	v_lshlrev_b32_e32 v10, 16, v133
	v_and_b32_e32 v11, 0xffff0000, v133
	v_pk_add_f32 v[10:11], v[12:13], v[10:11]
	v_pk_add_f32 v[16:17], v[108:109], v[16:17]
	v_pk_add_f32 v[20:21], v[96:97], v[10:11]
	v_cvt_pk_bf16_f32 v10, v14, v15
	v_cvt_pk_bf16_f32 v11, v16, v17
	v_and_b32_e32 v15, 0xffff0000, v10
	v_lshlrev_b32_e32 v14, 16, v10
	v_and_b32_e32 v17, 0xffff0000, v11
	v_mul_f32_e32 v15, v15, v15
	v_cvt_pk_bf16_f32 v12, v18, v19
	v_lshlrev_b32_e32 v16, 16, v11
	v_fmac_f32_e32 v15, v14, v14
	v_mul_f32_e32 v14, v17, v17
	v_and_b32_e32 v19, 0xffff0000, v12
	v_fmac_f32_e32 v14, v16, v16
	v_cvt_pk_bf16_f32 v13, v20, v21
	v_lshlrev_b32_e32 v18, 16, v12
	v_add_f32_e32 v14, v15, v14
	v_mul_f32_e32 v15, v19, v19
	v_and_b32_e32 v21, 0xffff0000, v13
	v_fmac_f32_e32 v15, v18, v18
	v_lshlrev_b32_e32 v20, 16, v13
	v_add_f32_e32 v14, v15, v14
	v_mul_f32_e32 v15, v21, v21
	v_fmac_f32_e32 v15, v20, v20
	v_add_f32_e32 v16, v15, v14
	s_waitcnt vmcnt(21)
	v_lshlrev_b32_e32 v14, 16, v122
	v_and_b32_e32 v15, 0xffff0000, v122
	v_pk_add_f32 v[6:7], v[6:7], v[14:15]
	v_lshlrev_b32_e32 v14, 16, v123
	v_and_b32_e32 v15, 0xffff0000, v123
	v_pk_add_f32 v[8:9], v[8:9], v[14:15]
	v_lshlrev_b32_e32 v14, 16, v124
	v_and_b32_e32 v15, 0xffff0000, v124
	v_pk_add_f32 v[2:3], v[2:3], v[14:15]
	v_lshlrev_b32_e32 v14, 16, v125
	v_and_b32_e32 v15, 0xffff0000, v125
	v_pk_add_f32 v[6:7], v[102:103], v[6:7]
	v_pk_add_f32 v[4:5], v[4:5], v[14:15]
	v_pk_add_f32 v[2:3], v[90:91], v[2:3]
	v_pk_add_f32 v[14:15], v[92:93], v[4:5]
	v_cvt_pk_bf16_f32 v4, v6, v7
	v_pk_add_f32 v[8:9], v[104:105], v[8:9]
	v_cvt_pk_bf16_f32 v6, v2, v3
	v_and_b32_e32 v3, 0xffff0000, v4
	v_cvt_pk_bf16_f32 v5, v8, v9
	v_lshlrev_b32_e32 v2, 16, v4
	v_mul_f32_e32 v3, v3, v3
	v_and_b32_e32 v9, 0xffff0000, v5
	v_fmac_f32_e32 v3, v2, v2
	v_lshlrev_b32_e32 v8, 16, v5
	v_add_f32_e32 v2, v3, v16
	v_mul_f32_e32 v3, v9, v9
	v_cvt_pk_bf16_f32 v7, v14, v15
	v_and_b32_e32 v15, 0xffff0000, v6
	v_fmac_f32_e32 v3, v8, v8
	v_lshlrev_b32_e32 v14, 16, v6
	v_add_f32_e32 v2, v3, v2
	v_mul_f32_e32 v3, v15, v15
	v_and_b32_e32 v18, 0xffff0000, v7
	v_fmac_f32_e32 v3, v14, v14
	v_lshlrev_b32_e32 v17, 16, v7
	v_add_f32_e32 v2, v3, v2
	v_mul_f32_e32 v3, v18, v18
	v_fmac_f32_e32 v3, v17, v17
	v_add_f32_e32 v2, v3, v2
	v_mov_b32_e32 v3, v2
	s_nop 1
	v_permlane16_swap_b32_e32 v3, v2
	v_lshlrev_b64 v[8:9], 11, v[226:227]
	v_lshl_add_u64 v[8:9], s[88:89], 0, v[8:9]
	v_lshl_add_u64 v[8:9], v[224:225], 1, v[8:9]
	global_store_dwordx4 v[8:9], v[10:13], off
	global_store_dwordx4 v[8:9], v[4:7], off offset:256
	s_waitcnt lgkmcnt(0)
	v_add_f32_e32 v2, v2, v3
	v_mov_b32_e32 v3, v2
	s_nop 1
	v_permlane32_swap_b32_e32 v3, v2
	s_and_saveexec_b64 s[42:43], vcc
	s_cbranch_execz .LBB0_847
	v_lshlrev_b64 v[4:5], 6, v[226:227]
	v_lshl_add_u64 v[4:5], s[68:69], 0, v[4:5]
	v_lshl_add_u64 v[4:5], s[10:11], 2, v[4:5]
	s_lshl_b32 s76, s54, 2
	v_lshl_add_u64 v[4:5], v[4:5], 0, s[76:77]
	s_waitcnt lgkmcnt(0)
	v_add_f32_e32 v2, v2, v3
	global_store_dword v[4:5], v2, off
